# all six GEMM loops: LDS-DMA addressing via SGPR base + 32-bit VGPR offset (saddr) instead of 16 per-iteration v_lshl_add_u64; on top of attention setprio
# speedup vs baseline: 1.0019x; 1.0019x over previous
; #define PG8_STAGE(bufoff, gbase, voff) do { _Pragma("unroll") for (int _i = 0; _i < 2; ++_i) \
;         __builtin_amdgcn_global_load_lds((const unsigned*)((const char*)(gbase) + (voff)[_i]), (PG8_LAS unsigned*)(lds + (bufoff) + ldsw + _i * 8192), 16, 0, 0); } while (0)
; #define PG8_LDA(dst, b, h) do { _Pragma("unroll") for (int m = 0; m < 4; ++m) _Pragma("unroll") for (int k = 0; k < 2; ++k) dst[m][k] = *(const PG8_LAS bf16x8*)(lds + PG8_SA(b, h) + aoff + m * 2048 + k * 1024); } while (0)
; #define PG8_LDB(dst, b, h) do { _Pragma("unroll") for (int n = 0; n < 2; ++n) _Pragma("unroll") for (int k = 0; k < 2; ++k) dst[n][k] = *(const PG8_LAS bf16x8*)(lds + PG8_SB(b, h) + boff + n * 2048 + k * 1024); } while (0)
; #define PG8_MMA(ai, bj, At, Bt) do { __builtin_amdgcn_s_setprio(1); _Pragma("unroll") for (int m = 0; m < 4; ++m) _Pragma("unroll") for (int n = 0; n < 2; ++n) _Pragma("unroll") for (int k = 0; k < 2; ++k) \
;         acc[ai][bj][m][n] = __builtin_amdgcn_mfma_f32_16x16x32_bf16(Bt[n][k], At[m][k], acc[ai][bj][m][n], 0, 0, 0); __builtin_amdgcn_s_setprio(0); } while (0)
; #define PG8_WAIT_V(n) asm volatile("s_waitcnt vmcnt(" #n ")" ::: "memory")
; #define PG8_WAIT_L(n) asm volatile("s_waitcnt lgkmcnt(" #n ")" ::: "memory")
; #define PG8_BAR __builtin_amdgcn_s_barrier()
; #define PG8_SCHED __builtin_amdgcn_sched_barrier(0)
; template <class Epi, class Sched, bool ALIGN_EPI = false, bool SP2 = false>
; __device__ __forceinline__ void gemm_phase(PG8_LAS unsigned char* lds, const Gemm g, const Sched& S, const Epi& E) {
;     ...
;             const char* a2 = last ? nA : cA + (size_t)(t + 2) * kstep; const char* b2 = last ? nB : cB + (size_t)(t + 2) * kstep;
;             const char* a3 = a2 + kstep; const char* b3 = b2 + kstep;
;             if (last && has_next) S.a_ready(nxt);
;             if constexpr (SP2) {
;             PG8_LDB(B0, 0, 0); PG8_LDB(B1, 0, 1); PG8_SCHED; PG8_LDA(At, 0, 0); PG8_STAGE(PG8_SA(1, 1), a1 + hstep, voffA);
;             PG8_WAIT_V(8); PG8_WAIT_L(0); PG8_BAR; PG8_MMA(0, 0, At, B0); PG8_MMA(0, 1, At, B1); PG8_BAR; PG8_SCHED;
;             PG8_LDA(At, 0, 1); PG8_STAGE(PG8_SB(0, 0), b2, voffB); PG8_STAGE(PG8_SB(0, 1), b2 + hstep, voffB); PG8_STAGE(PG8_SA(0, 0), a2, voffA);
;             PG8_WAIT_V(8); PG8_WAIT_L(0); PG8_BAR; PG8_MMA(1, 0, At, B0); PG8_MMA(1, 1, At, B1); PG8_BAR; PG8_SCHED;
.LBB0_99:
	ds_read_b128 v[158:161], v152
	ds_read_b128 v[168:171], v152 offset:1024
	ds_read_b128 v[172:175], v152 offset:2048
	ds_read_b128 v[176:179], v152 offset:3072
	ds_read_b128 v[180:183], v153
	ds_read_b128 v[184:187], v153 offset:1024
	ds_read_b128 v[188:191], v153 offset:2048
	ds_read_b128 v[192:195], v153 offset:3072
	s_add_u32 s46, s6, 0xfff80080
	s_addc_u32 s47, s7, -1
	s_cmp_eq_u32 s74, 28
	s_cselect_b32 s49, s39, s47
	s_cselect_b32 s48, s70, s46
	s_cselect_b32 s47, s37, s73
	s_cselect_b32 s46, s71, s72
	s_add_i32 m0, s45, 0xc000
	ds_read_b128 v[196:199], v154
	ds_read_b128 v[200:203], v154 offset:1024
	ds_read_b128 v[204:207], v154 offset:2048
	ds_read_b128 v[208:211], v154 offset:3072
	ds_read_b128 v[212:215], v154 offset:4096
	ds_read_b128 v[216:219], v154 offset:5120
	ds_read_b128 v[220:223], v154 offset:6144
	ds_read_b128 v[224:227], v154 offset:7168
	global_load_lds_dwordx4 v138, s[6:7]
	s_add_i32 m0, s45, 0xe000
	s_nop 0
	global_load_lds_dwordx4 v140, s[6:7]
	s_waitcnt vmcnt(8)
	s_waitcnt lgkmcnt(0)
	s_barrier
	s_setprio 1
	s_waitcnt lgkmcnt(0)
	v_mfma_f32_16x16x32_bf16 v[124:127], v[158:161], v[196:199], v[124:127]
	v_mfma_f32_16x16x32_bf16 v[120:123], v[172:175], v[196:199], v[120:123]
	v_mfma_f32_16x16x32_bf16 v[108:111], v[158:161], v[204:207], v[108:111]
	v_mfma_f32_16x16x32_bf16 v[104:107], v[172:175], v[204:207], v[104:107]
	v_mfma_f32_16x16x32_bf16 v[92:95], v[158:161], v[212:215], v[92:95]
	v_mfma_f32_16x16x32_bf16 v[88:91], v[172:175], v[212:215], v[88:91]
	v_mfma_f32_16x16x32_bf16 v[76:79], v[158:161], v[220:223], v[76:79]
	v_mfma_f32_16x16x32_bf16 v[72:75], v[172:175], v[220:223], v[72:75]
	v_mfma_f32_16x16x32_bf16 v[124:127], v[168:171], v[200:203], v[124:127]
	v_mfma_f32_16x16x32_bf16 v[120:123], v[176:179], v[200:203], v[120:123]
	v_mfma_f32_16x16x32_bf16 v[108:111], v[168:171], v[208:211], v[108:111]
	v_mfma_f32_16x16x32_bf16 v[104:107], v[176:179], v[208:211], v[104:107]
	v_mfma_f32_16x16x32_bf16 v[92:95], v[168:171], v[216:219], v[92:95]
	v_mfma_f32_16x16x32_bf16 v[88:91], v[176:179], v[216:219], v[88:91]
	v_mfma_f32_16x16x32_bf16 v[76:79], v[168:171], v[224:227], v[76:79]
	v_mfma_f32_16x16x32_bf16 v[72:75], v[176:179], v[224:227], v[72:75]
	s_setprio 0
	s_setprio 1
	v_mfma_f32_16x16x32_bf16 v[116:119], v[180:183], v[196:199], v[116:119]
	v_mfma_f32_16x16x32_bf16 v[112:115], v[188:191], v[196:199], v[112:115]
	v_mfma_f32_16x16x32_bf16 v[100:103], v[180:183], v[204:207], v[100:103]
	v_mfma_f32_16x16x32_bf16 v[96:99], v[188:191], v[204:207], v[96:99]
	v_mfma_f32_16x16x32_bf16 v[84:87], v[180:183], v[212:215], v[84:87]
	v_mfma_f32_16x16x32_bf16 v[80:83], v[188:191], v[212:215], v[80:83]
	v_mfma_f32_16x16x32_bf16 v[68:71], v[180:183], v[220:223], v[68:71]
	v_mfma_f32_16x16x32_bf16 v[64:67], v[188:191], v[220:223], v[64:67]
	v_mfma_f32_16x16x32_bf16 v[116:119], v[184:187], v[200:203], v[116:119]
	v_mfma_f32_16x16x32_bf16 v[112:115], v[192:195], v[200:203], v[112:115]
	v_mfma_f32_16x16x32_bf16 v[100:103], v[184:187], v[208:211], v[100:103]
	v_mfma_f32_16x16x32_bf16 v[96:99], v[192:195], v[208:211], v[96:99]
	v_mfma_f32_16x16x32_bf16 v[84:87], v[184:187], v[216:219], v[84:87]
	v_mfma_f32_16x16x32_bf16 v[80:83], v[192:195], v[216:219], v[80:83]
	v_mfma_f32_16x16x32_bf16 v[68:71], v[184:187], v[224:227], v[68:71]
	v_mfma_f32_16x16x32_bf16 v[64:67], v[192:195], v[224:227], v[64:67]
	s_setprio 0
	s_barrier
	s_add_u32 s98, s46, 0x80
	s_addc_u32 s99, s47, 0
	s_add_u32 s100, s48, 0x80
	s_addc_u32 s101, s49, 0
	s_add_i32 s75, s63, s50
	s_mov_b32 m0, s75
	ds_read_b128 v[196:199], v154 offset:16384
	ds_read_b128 v[200:203], v154 offset:17408
	ds_read_b128 v[204:207], v154 offset:18432
	ds_read_b128 v[208:211], v154 offset:19456
	ds_read_b128 v[212:215], v154 offset:20480
	ds_read_b128 v[216:219], v154 offset:21504
	ds_read_b128 v[220:223], v154 offset:22528
	ds_read_b128 v[224:227], v154 offset:23552
	global_load_lds_dwordx4 v134, s[46:47]
	s_add_i32 m0, s75, 0x2000
	s_add_u32 s76, s46, 0x80000
	s_addc_u32 s77, s47, 0
	s_add_i32 s75, s64, s50
	global_load_lds_dwordx4 v130, s[46:47]
	s_mov_b32 m0, s75
	s_nop 0
	global_load_lds_dwordx4 v134, s[76:77]
	s_add_i32 m0, s75, 0x2000
	s_nop 0
	global_load_lds_dwordx4 v130, s[76:77]
	s_mov_b32 m0, s45
	s_nop 0
	global_load_lds_dwordx4 v136, s[48:49]
	s_mov_b32 m0, s53
	s_nop 0
	global_load_lds_dwordx4 v132, s[48:49]
	s_waitcnt vmcnt(8)
	s_waitcnt lgkmcnt(0)
	s_barrier
	s_setprio 1
	s_waitcnt lgkmcnt(0)
	v_mfma_f32_16x16x32_bf16 v[60:63], v[158:161], v[196:199], v[60:63]
	v_mfma_f32_16x16x32_bf16 v[56:59], v[172:175], v[196:199], v[56:59]
	v_mfma_f32_16x16x32_bf16 v[48:51], v[158:161], v[204:207], v[48:51]
	v_mfma_f32_16x16x32_bf16 v[40:43], v[172:175], v[204:207], v[40:43]
	v_mfma_f32_16x16x32_bf16 v[32:35], v[158:161], v[212:215], v[32:35]
	v_mfma_f32_16x16x32_bf16 v[24:27], v[172:175], v[212:215], v[24:27]
	v_mfma_f32_16x16x32_bf16 v[16:19], v[158:161], v[220:223], v[16:19]
	v_mfma_f32_16x16x32_bf16 v[8:11], v[172:175], v[220:223], v[8:11]
	v_mfma_f32_16x16x32_bf16 v[60:63], v[168:171], v[200:203], v[60:63]
	v_mfma_f32_16x16x32_bf16 v[56:59], v[176:179], v[200:203], v[56:59]
	v_mfma_f32_16x16x32_bf16 v[48:51], v[168:171], v[208:211], v[48:51]
	v_mfma_f32_16x16x32_bf16 v[40:43], v[176:179], v[208:211], v[40:43]
	v_mfma_f32_16x16x32_bf16 v[32:35], v[168:171], v[216:219], v[32:35]
	v_mfma_f32_16x16x32_bf16 v[24:27], v[176:179], v[216:219], v[24:27]
	v_mfma_f32_16x16x32_bf16 v[16:19], v[168:171], v[224:227], v[16:19]
	v_mfma_f32_16x16x32_bf16 v[8:11], v[176:179], v[224:227], v[8:11]
	s_setprio 0
	s_setprio 1
	v_mfma_f32_16x16x32_bf16 v[52:55], v[180:183], v[196:199], v[52:55]
	v_mfma_f32_16x16x32_bf16 v[44:47], v[188:191], v[196:199], v[44:47]
	v_mfma_f32_16x16x32_bf16 v[36:39], v[180:183], v[204:207], v[36:39]
	v_mfma_f32_16x16x32_bf16 v[28:31], v[188:191], v[204:207], v[28:31]
	v_mfma_f32_16x16x32_bf16 v[20:23], v[180:183], v[212:215], v[20:23]
	v_mfma_f32_16x16x32_bf16 v[12:15], v[188:191], v[212:215], v[12:15]
	v_mfma_f32_16x16x32_bf16 v[4:7], v[180:183], v[220:223], v[4:7]
	v_mfma_f32_16x16x32_bf16 v[0:3], v[188:191], v[220:223], v[0:3]
	v_mfma_f32_16x16x32_bf16 v[52:55], v[184:187], v[200:203], v[52:55]
	v_mfma_f32_16x16x32_bf16 v[44:47], v[192:195], v[200:203], v[44:47]
	v_mfma_f32_16x16x32_bf16 v[36:39], v[184:187], v[208:211], v[36:39]
	v_mfma_f32_16x16x32_bf16 v[28:31], v[192:195], v[208:211], v[28:31]
	v_mfma_f32_16x16x32_bf16 v[20:23], v[184:187], v[216:219], v[20:23]
	v_mfma_f32_16x16x32_bf16 v[12:15], v[192:195], v[216:219], v[12:15]
	v_mfma_f32_16x16x32_bf16 v[4:7], v[184:187], v[224:227], v[4:7]
	v_mfma_f32_16x16x32_bf16 v[0:3], v[192:195], v[224:227], v[0:3]
	s_setprio 0
	s_barrier
; #define PG8_STAGE(bufoff, gbase, voff) do { _Pragma("unroll") for (int _i = 0; _i < 2; ++_i) \
;         __builtin_amdgcn_global_load_lds((const unsigned*)((const char*)(gbase) + (voff)[_i]), (PG8_LAS unsigned*)(lds + (bufoff) + ldsw + _i * 8192), 16, 0, 0); } while (0)
; #define PG8_LDA(dst, b, h) do { _Pragma("unroll") for (int m = 0; m < 4; ++m) _Pragma("unroll") for (int k = 0; k < 2; ++k) dst[m][k] = *(const PG8_LAS bf16x8*)(lds + PG8_SA(b, h) + aoff + m * 2048 + k * 1024); } while (0)
; #define PG8_LDB(dst, b, h) do { _Pragma("unroll") for (int n = 0; n < 2; ++n) _Pragma("unroll") for (int k = 0; k < 2; ++k) dst[n][k] = *(const PG8_LAS bf16x8*)(lds + PG8_SB(b, h) + boff + n * 2048 + k * 1024); } while (0)
; #define PG8_MMA(ai, bj, At, Bt) do { __builtin_amdgcn_s_setprio(1); _Pragma("unroll") for (int m = 0; m < 4; ++m) _Pragma("unroll") for (int n = 0; n < 2; ++n) _Pragma("unroll") for (int k = 0; k < 2; ++k) \
;         acc[ai][bj][m][n] = __builtin_amdgcn_mfma_f32_16x16x32_bf16(Bt[n][k], At[m][k], acc[ai][bj][m][n], 0, 0, 0); __builtin_amdgcn_s_setprio(0); } while (0)
; #define PG8_WAIT_V(n) asm volatile("s_waitcnt vmcnt(" #n ")" ::: "memory")
; #define PG8_WAIT_L(n) asm volatile("s_waitcnt lgkmcnt(" #n ")" ::: "memory")
; #define PG8_BAR __builtin_amdgcn_s_barrier()
; #define PG8_SCHED __builtin_amdgcn_sched_barrier(0)
; template <class Epi, class Sched, bool ALIGN_EPI = false, bool SP2 = false>
; __device__ __forceinline__ void gemm_phase(PG8_LAS unsigned char* lds, const Gemm g, const Sched& S, const Epi& E) {
;     ...
;             PG8_LDB(B0, 1, 0); PG8_LDB(B1, 1, 1); PG8_SCHED; PG8_LDA(At, 1, 0); PG8_STAGE(PG8_SA(0, 1), a2 + hstep, voffA);
;             PG8_WAIT_V(8); PG8_WAIT_L(0); PG8_BAR; PG8_MMA(0, 0, At, B0); PG8_MMA(0, 1, At, B1); PG8_BAR; PG8_SCHED;
;             PG8_LDA(At, 1, 1); PG8_STAGE(PG8_SB(1, 0), b3, voffB); PG8_STAGE(PG8_SB(1, 1), b3 + hstep, voffB); PG8_STAGE(PG8_SA(1, 0), a3, voffA);
;             PG8_WAIT_V(8); PG8_WAIT_L(0); PG8_BAR; PG8_MMA(1, 0, At, B0); PG8_MMA(1, 1, At, B1); PG8_BAR; PG8_SCHED;
	s_add_i32 s75, 0, 0x18000
	v_add_u32_e32 v146, s75, v150
	s_add_i32 s76, 0, 0x1c000
	ds_read_b128 v[158:161], v146
	ds_read_b128 v[168:171], v146 offset:1024
	ds_read_b128 v[172:175], v146 offset:2048
	ds_read_b128 v[176:179], v146 offset:3072
	v_add_u32_e32 v146, s76, v150
	ds_read_b128 v[180:183], v146
	ds_read_b128 v[184:187], v146 offset:1024
	ds_read_b128 v[188:191], v146 offset:2048
	ds_read_b128 v[192:195], v146 offset:3072
	s_add_u32 s48, s48, 0x80000
	s_addc_u32 s49, s49, 0
	s_mov_b32 m0, s54
	ds_read_b128 v[196:199], v154 offset:32768
	ds_read_b128 v[200:203], v154 offset:33792
	ds_read_b128 v[204:207], v154 offset:34816
	ds_read_b128 v[208:211], v154 offset:35840
	ds_read_b128 v[212:215], v154 offset:36864
	ds_read_b128 v[216:219], v154 offset:37888
	ds_read_b128 v[220:223], v154 offset:38912
	ds_read_b128 v[224:227], v154 offset:39936
	global_load_lds_dwordx4 v136, s[48:49]
	s_mov_b32 m0, s55
	s_nop 0
	global_load_lds_dwordx4 v132, s[48:49]
	s_waitcnt vmcnt(8)
	s_waitcnt lgkmcnt(0)
	s_barrier
	s_setprio 1
	s_waitcnt lgkmcnt(0)
	v_mfma_f32_16x16x32_bf16 v[124:127], v[158:161], v[196:199], v[124:127]
	v_mfma_f32_16x16x32_bf16 v[120:123], v[172:175], v[196:199], v[120:123]
	v_mfma_f32_16x16x32_bf16 v[108:111], v[158:161], v[204:207], v[108:111]
	v_mfma_f32_16x16x32_bf16 v[104:107], v[172:175], v[204:207], v[104:107]
	v_mfma_f32_16x16x32_bf16 v[92:95], v[158:161], v[212:215], v[92:95]
	v_mfma_f32_16x16x32_bf16 v[88:91], v[172:175], v[212:215], v[88:91]
	v_mfma_f32_16x16x32_bf16 v[76:79], v[158:161], v[220:223], v[76:79]
	v_mfma_f32_16x16x32_bf16 v[72:75], v[172:175], v[220:223], v[72:75]
	v_mfma_f32_16x16x32_bf16 v[124:127], v[168:171], v[200:203], v[124:127]
	v_mfma_f32_16x16x32_bf16 v[120:123], v[176:179], v[200:203], v[120:123]
	v_mfma_f32_16x16x32_bf16 v[108:111], v[168:171], v[208:211], v[108:111]
	v_mfma_f32_16x16x32_bf16 v[104:107], v[176:179], v[208:211], v[104:107]
	v_mfma_f32_16x16x32_bf16 v[92:95], v[168:171], v[216:219], v[92:95]
	v_mfma_f32_16x16x32_bf16 v[88:91], v[176:179], v[216:219], v[88:91]
	v_mfma_f32_16x16x32_bf16 v[76:79], v[168:171], v[224:227], v[76:79]
	v_mfma_f32_16x16x32_bf16 v[72:75], v[176:179], v[224:227], v[72:75]
	s_setprio 0
	s_setprio 1
	v_mfma_f32_16x16x32_bf16 v[116:119], v[180:183], v[196:199], v[116:119]
	v_mfma_f32_16x16x32_bf16 v[112:115], v[188:191], v[196:199], v[112:115]
	v_mfma_f32_16x16x32_bf16 v[100:103], v[180:183], v[204:207], v[100:103]
	v_mfma_f32_16x16x32_bf16 v[96:99], v[188:191], v[204:207], v[96:99]
	v_mfma_f32_16x16x32_bf16 v[84:87], v[180:183], v[212:215], v[84:87]
	v_mfma_f32_16x16x32_bf16 v[80:83], v[188:191], v[212:215], v[80:83]
	v_mfma_f32_16x16x32_bf16 v[68:71], v[180:183], v[220:223], v[68:71]
	v_mfma_f32_16x16x32_bf16 v[64:67], v[188:191], v[220:223], v[64:67]
	v_mfma_f32_16x16x32_bf16 v[116:119], v[184:187], v[200:203], v[116:119]
	v_mfma_f32_16x16x32_bf16 v[112:115], v[192:195], v[200:203], v[112:115]
	v_mfma_f32_16x16x32_bf16 v[100:103], v[184:187], v[208:211], v[100:103]
	v_mfma_f32_16x16x32_bf16 v[96:99], v[192:195], v[208:211], v[96:99]
	v_mfma_f32_16x16x32_bf16 v[84:87], v[184:187], v[216:219], v[84:87]
	v_mfma_f32_16x16x32_bf16 v[80:83], v[192:195], v[216:219], v[80:83]
	v_mfma_f32_16x16x32_bf16 v[68:71], v[184:187], v[224:227], v[68:71]
	v_mfma_f32_16x16x32_bf16 v[64:67], v[192:195], v[224:227], v[64:67]
	s_setprio 0
	s_barrier
	s_add_i32 s48, s75, s50
	s_mov_b32 m0, s48
	ds_read_b128 v[196:199], v154 offset:49152
	ds_read_b128 v[200:203], v154 offset:50176
	ds_read_b128 v[204:207], v154 offset:51200
	ds_read_b128 v[208:211], v154 offset:52224
	ds_read_b128 v[212:215], v154 offset:53248
	ds_read_b128 v[216:219], v154 offset:54272
	ds_read_b128 v[220:223], v154 offset:55296
	ds_read_b128 v[224:227], v154 offset:56320
	global_load_lds_dwordx4 v134, s[98:99]
	s_add_i32 m0, s48, 0x2000
	s_add_u32 s46, s46, 0x80080
	s_addc_u32 s47, s47, 0
	s_add_i32 s48, s76, s50
	global_load_lds_dwordx4 v130, s[98:99]
	s_mov_b32 m0, s48
	s_nop 0
	global_load_lds_dwordx4 v134, s[46:47]
	s_add_i32 m0, s48, 0x2000
	s_nop 0
	global_load_lds_dwordx4 v130, s[46:47]
	s_mov_b32 m0, s59
	s_nop 0
	global_load_lds_dwordx4 v136, s[100:101]
	s_mov_b32 m0, s60
	s_nop 0
	global_load_lds_dwordx4 v132, s[100:101]
	s_waitcnt vmcnt(8)
	s_waitcnt lgkmcnt(0)
	s_barrier
	s_setprio 1
	s_waitcnt lgkmcnt(0)
	v_mfma_f32_16x16x32_bf16 v[60:63], v[158:161], v[196:199], v[60:63]
	v_mfma_f32_16x16x32_bf16 v[56:59], v[172:175], v[196:199], v[56:59]
	v_mfma_f32_16x16x32_bf16 v[48:51], v[158:161], v[204:207], v[48:51]
	v_mfma_f32_16x16x32_bf16 v[40:43], v[172:175], v[204:207], v[40:43]
	v_mfma_f32_16x16x32_bf16 v[32:35], v[158:161], v[212:215], v[32:35]
	v_mfma_f32_16x16x32_bf16 v[24:27], v[172:175], v[212:215], v[24:27]
	v_mfma_f32_16x16x32_bf16 v[16:19], v[158:161], v[220:223], v[16:19]
	v_mfma_f32_16x16x32_bf16 v[8:11], v[172:175], v[220:223], v[8:11]
	v_mfma_f32_16x16x32_bf16 v[60:63], v[168:171], v[200:203], v[60:63]
	v_mfma_f32_16x16x32_bf16 v[56:59], v[176:179], v[200:203], v[56:59]
	v_mfma_f32_16x16x32_bf16 v[48:51], v[168:171], v[208:211], v[48:51]
	v_mfma_f32_16x16x32_bf16 v[40:43], v[176:179], v[208:211], v[40:43]
	v_mfma_f32_16x16x32_bf16 v[32:35], v[168:171], v[216:219], v[32:35]
	v_mfma_f32_16x16x32_bf16 v[24:27], v[176:179], v[216:219], v[24:27]
	v_mfma_f32_16x16x32_bf16 v[16:19], v[168:171], v[224:227], v[16:19]
	v_mfma_f32_16x16x32_bf16 v[8:11], v[176:179], v[224:227], v[8:11]
	s_setprio 0
	s_setprio 1
	v_mfma_f32_16x16x32_bf16 v[52:55], v[180:183], v[196:199], v[52:55]
	v_mfma_f32_16x16x32_bf16 v[44:47], v[188:191], v[196:199], v[44:47]
	v_mfma_f32_16x16x32_bf16 v[36:39], v[180:183], v[204:207], v[36:39]
	v_mfma_f32_16x16x32_bf16 v[28:31], v[188:191], v[204:207], v[28:31]
	v_mfma_f32_16x16x32_bf16 v[20:23], v[180:183], v[212:215], v[20:23]
	v_mfma_f32_16x16x32_bf16 v[12:15], v[188:191], v[212:215], v[12:15]
	v_mfma_f32_16x16x32_bf16 v[4:7], v[180:183], v[220:223], v[4:7]
	v_mfma_f32_16x16x32_bf16 v[0:3], v[188:191], v[220:223], v[0:3]
	v_mfma_f32_16x16x32_bf16 v[52:55], v[184:187], v[200:203], v[52:55]
	v_mfma_f32_16x16x32_bf16 v[44:47], v[192:195], v[200:203], v[44:47]
	v_mfma_f32_16x16x32_bf16 v[36:39], v[184:187], v[208:211], v[36:39]
	v_mfma_f32_16x16x32_bf16 v[28:31], v[192:195], v[208:211], v[28:31]
	v_mfma_f32_16x16x32_bf16 v[20:23], v[184:187], v[216:219], v[20:23]
	v_mfma_f32_16x16x32_bf16 v[12:15], v[192:195], v[216:219], v[12:15]
	v_mfma_f32_16x16x32_bf16 v[4:7], v[184:187], v[224:227], v[4:7]
	v_mfma_f32_16x16x32_bf16 v[0:3], v[192:195], v[224:227], v[0:3]
	s_setprio 0
	s_barrier
	s_add_i32 s74, s74, 2
	s_add_u32 s6, s6, 0x100
	s_addc_u32 s7, s7, 0
	s_add_u32 s72, s72, 0x100
	s_addc_u32 s73, s73, 0
	s_cmp_gt_u32 s74, 29
	s_cbranch_scc0 .LBB0_99
	s_and_b64 vcc, exec, s[18:19]
	s_cbranch_vccz .LBB0_102
	s_barrier

; #define PG8_STAGE(bufoff, gbase, voff) do { _Pragma("unroll") for (int _i = 0; _i < 2; ++_i) \
;         __builtin_amdgcn_global_load_lds((const unsigned*)((const char*)(gbase) + (voff)[_i]), (PG8_LAS unsigned*)(lds + (bufoff) + ldsw + _i * 8192), 16, 0, 0); } while (0)
; #define PG8_LDA(dst, b, h) do { _Pragma("unroll") for (int m = 0; m < 4; ++m) _Pragma("unroll") for (int k = 0; k < 2; ++k) dst[m][k] = *(const PG8_LAS bf16x8*)(lds + PG8_SA(b, h) + aoff + m * 2048 + k * 1024); } while (0)
; #define PG8_LDB(dst, b, h) do { _Pragma("unroll") for (int n = 0; n < 2; ++n) _Pragma("unroll") for (int k = 0; k < 2; ++k) dst[n][k] = *(const PG8_LAS bf16x8*)(lds + PG8_SB(b, h) + boff + n * 2048 + k * 1024); } while (0)
; #define PG8_MMA(ai, bj, At, Bt) do { __builtin_amdgcn_s_setprio(1); _Pragma("unroll") for (int m = 0; m < 4; ++m) _Pragma("unroll") for (int n = 0; n < 2; ++n) _Pragma("unroll") for (int k = 0; k < 2; ++k) \
;         acc[ai][bj][m][n] = __builtin_amdgcn_mfma_f32_16x16x32_bf16(Bt[n][k], At[m][k], acc[ai][bj][m][n], 0, 0, 0); __builtin_amdgcn_s_setprio(0); } while (0)
; #define PG8_WAIT_V(n) asm volatile("s_waitcnt vmcnt(" #n ")" ::: "memory")
; #define PG8_WAIT_L(n) asm volatile("s_waitcnt lgkmcnt(" #n ")" ::: "memory")
; #define PG8_BAR __builtin_amdgcn_s_barrier()
; #define PG8_SCHED __builtin_amdgcn_sched_barrier(0)
; template <class Epi, class Sched, bool ALIGN_EPI = false, bool SP2 = false>
; __device__ __forceinline__ void gemm_phase(PG8_LAS unsigned char* lds, const Gemm g, const Sched& S, const Epi& E) {
;     ...
;             const char* a2 = last ? nA : cA + (size_t)(t + 2) * kstep; const char* b2 = last ? nB : cB + (size_t)(t + 2) * kstep;
;             const char* a3 = a2 + kstep; const char* b3 = b2 + kstep;
;             if (last && has_next) S.a_ready(nxt);
;             if constexpr (SP2) {
;             PG8_LDB(B0, 0, 0); PG8_LDB(B1, 0, 1); PG8_SCHED; PG8_LDA(At, 0, 0); PG8_STAGE(PG8_SA(1, 1), a1 + hstep, voffA);
;             PG8_WAIT_V(8); PG8_WAIT_L(0); PG8_BAR; PG8_MMA(0, 0, At, B0); PG8_MMA(0, 1, At, B1); PG8_BAR; PG8_SCHED;
;             PG8_LDA(At, 0, 1); PG8_STAGE(PG8_SB(0, 0), b2, voffB); PG8_STAGE(PG8_SB(0, 1), b2 + hstep, voffB); PG8_STAGE(PG8_SA(0, 0), a2, voffA);
;             PG8_WAIT_V(8); PG8_WAIT_L(0); PG8_BAR; PG8_MMA(1, 0, At, B0); PG8_MMA(1, 1, At, B1); PG8_BAR; PG8_SCHED;
.LBB0_319:
	v_add_u32_e32 v172, s65, v174
	ds_read_b128 v[178:181], v172
	ds_read_b128 v[188:191], v172 offset:1024
	ds_read_b128 v[192:195], v172 offset:2048
	ds_read_b128 v[196:199], v172 offset:3072
	v_add_u32_e32 v172, s66, v174
	ds_read_b128 v[200:203], v172
	ds_read_b128 v[204:207], v172 offset:1024
	ds_read_b128 v[208:211], v172 offset:2048
	ds_read_b128 v[212:215], v172 offset:3072
	s_add_u32 s50, s48, 0xfff80080
	s_addc_u32 s51, s49, -1
	s_cmp_eq_u32 s69, 28
	s_cselect_b32 s53, s16, s51
	s_cselect_b32 s52, s39, s50
	s_cselect_b32 s51, s37, s68
	s_cselect_b32 s50, s45, s47
	s_add_i32 m0, s56, 0xc000
	ds_read_b128 v[216:219], v176
	ds_read_b128 v[220:223], v176 offset:1024
	ds_read_b128 v[224:227], v176 offset:2048
	ds_read_b128 v[228:231], v176 offset:3072
	ds_read_b128 v[232:235], v176 offset:4096
	ds_read_b128 v[236:239], v176 offset:5120
	ds_read_b128 v[240:243], v176 offset:6144
	ds_read_b128 v[244:247], v176 offset:7168
	global_load_lds_dwordx4 v160, s[48:49]
	s_add_i32 m0, s56, 0xe000
	s_nop 0
	global_load_lds_dwordx4 v162, s[48:49]
	s_waitcnt vmcnt(8)
	s_waitcnt lgkmcnt(0)
	s_barrier
	s_setprio 1
	s_waitcnt lgkmcnt(0)
	v_mfma_f32_16x16x32_bf16 v[124:127], v[178:181], v[216:219], v[124:127]
	v_mfma_f32_16x16x32_bf16 v[120:123], v[192:195], v[216:219], v[120:123]
	v_mfma_f32_16x16x32_bf16 v[108:111], v[178:181], v[224:227], v[108:111]
	v_mfma_f32_16x16x32_bf16 v[104:107], v[192:195], v[224:227], v[104:107]
	v_mfma_f32_16x16x32_bf16 v[92:95], v[178:181], v[232:235], v[92:95]
	v_mfma_f32_16x16x32_bf16 v[88:91], v[192:195], v[232:235], v[88:91]
	v_mfma_f32_16x16x32_bf16 v[76:79], v[178:181], v[240:243], v[76:79]
	v_mfma_f32_16x16x32_bf16 v[72:75], v[192:195], v[240:243], v[72:75]
	v_mfma_f32_16x16x32_bf16 v[124:127], v[188:191], v[220:223], v[124:127]
	v_mfma_f32_16x16x32_bf16 v[120:123], v[196:199], v[220:223], v[120:123]
	v_mfma_f32_16x16x32_bf16 v[108:111], v[188:191], v[228:231], v[108:111]
	v_mfma_f32_16x16x32_bf16 v[104:107], v[196:199], v[228:231], v[104:107]
	v_mfma_f32_16x16x32_bf16 v[92:95], v[188:191], v[236:239], v[92:95]
	v_mfma_f32_16x16x32_bf16 v[88:91], v[196:199], v[236:239], v[88:91]
	v_mfma_f32_16x16x32_bf16 v[76:79], v[188:191], v[244:247], v[76:79]
	v_mfma_f32_16x16x32_bf16 v[72:75], v[196:199], v[244:247], v[72:75]
	s_setprio 0
	s_setprio 1
	v_mfma_f32_16x16x32_bf16 v[116:119], v[200:203], v[216:219], v[116:119]
	v_mfma_f32_16x16x32_bf16 v[112:115], v[208:211], v[216:219], v[112:115]
	v_mfma_f32_16x16x32_bf16 v[100:103], v[200:203], v[224:227], v[100:103]
	v_mfma_f32_16x16x32_bf16 v[96:99], v[208:211], v[224:227], v[96:99]
	v_mfma_f32_16x16x32_bf16 v[84:87], v[200:203], v[232:235], v[84:87]
	v_mfma_f32_16x16x32_bf16 v[80:83], v[208:211], v[232:235], v[80:83]
	v_mfma_f32_16x16x32_bf16 v[68:71], v[200:203], v[240:243], v[68:71]
	v_mfma_f32_16x16x32_bf16 v[64:67], v[208:211], v[240:243], v[64:67]
	v_mfma_f32_16x16x32_bf16 v[116:119], v[204:207], v[220:223], v[116:119]
	v_mfma_f32_16x16x32_bf16 v[112:115], v[212:215], v[220:223], v[112:115]
	v_mfma_f32_16x16x32_bf16 v[100:103], v[204:207], v[228:231], v[100:103]
	v_mfma_f32_16x16x32_bf16 v[96:99], v[212:215], v[228:231], v[96:99]
	v_mfma_f32_16x16x32_bf16 v[84:87], v[204:207], v[236:239], v[84:87]
	v_mfma_f32_16x16x32_bf16 v[80:83], v[212:215], v[236:239], v[80:83]
	v_mfma_f32_16x16x32_bf16 v[68:71], v[204:207], v[244:247], v[68:71]
	v_mfma_f32_16x16x32_bf16 v[64:67], v[212:215], v[244:247], v[64:67]
	s_setprio 0
	s_barrier
	s_add_u32 s98, s50, 0x80
	s_addc_u32 s99, s51, 0
	s_add_u32 s100, s52, 0x80
	s_addc_u32 s101, s53, 0
	s_add_i32 s70, s65, s55
	s_mov_b32 m0, s70
	ds_read_b128 v[216:219], v176 offset:16384
	ds_read_b128 v[220:223], v176 offset:17408
	ds_read_b128 v[224:227], v176 offset:18432
	ds_read_b128 v[228:231], v176 offset:19456
	ds_read_b128 v[232:235], v176 offset:20480
	ds_read_b128 v[236:239], v176 offset:21504
	ds_read_b128 v[240:243], v176 offset:22528
	ds_read_b128 v[244:247], v176 offset:23552
	global_load_lds_dwordx4 v130, s[50:51]
	s_add_i32 m0, s70, 0x2000
	s_add_u32 s70, s50, 0x80000
	s_addc_u32 s71, s51, 0
	s_add_i32 s72, s66, s55
	global_load_lds_dwordx4 v134, s[50:51]
	s_mov_b32 m0, s72
	s_nop 0
	global_load_lds_dwordx4 v130, s[70:71]
	s_add_i32 m0, s72, 0x2000
	s_nop 0
	global_load_lds_dwordx4 v134, s[70:71]
	s_mov_b32 m0, s56
	s_nop 0
	global_load_lds_dwordx4 v128, s[52:53]
	s_mov_b32 m0, s57
	s_nop 0
	global_load_lds_dwordx4 v132, s[52:53]
	s_waitcnt vmcnt(8)
	s_waitcnt lgkmcnt(0)
	s_barrier
	s_setprio 1
	s_waitcnt lgkmcnt(0)
	v_mfma_f32_16x16x32_bf16 v[60:63], v[178:181], v[216:219], v[60:63]
	v_mfma_f32_16x16x32_bf16 v[56:59], v[192:195], v[216:219], v[56:59]
	v_mfma_f32_16x16x32_bf16 v[44:47], v[178:181], v[224:227], v[44:47]
	v_mfma_f32_16x16x32_bf16 v[40:43], v[192:195], v[224:227], v[40:43]
	v_mfma_f32_16x16x32_bf16 v[28:31], v[178:181], v[232:235], v[28:31]
	v_mfma_f32_16x16x32_bf16 v[24:27], v[192:195], v[232:235], v[24:27]
	v_mfma_f32_16x16x32_bf16 v[12:15], v[178:181], v[240:243], v[12:15]
	v_mfma_f32_16x16x32_bf16 v[8:11], v[192:195], v[240:243], v[8:11]
	v_mfma_f32_16x16x32_bf16 v[60:63], v[188:191], v[220:223], v[60:63]
	v_mfma_f32_16x16x32_bf16 v[56:59], v[196:199], v[220:223], v[56:59]
	v_mfma_f32_16x16x32_bf16 v[44:47], v[188:191], v[228:231], v[44:47]
	v_mfma_f32_16x16x32_bf16 v[40:43], v[196:199], v[228:231], v[40:43]
	v_mfma_f32_16x16x32_bf16 v[28:31], v[188:191], v[236:239], v[28:31]
	v_mfma_f32_16x16x32_bf16 v[24:27], v[196:199], v[236:239], v[24:27]
	v_mfma_f32_16x16x32_bf16 v[12:15], v[188:191], v[244:247], v[12:15]
	v_mfma_f32_16x16x32_bf16 v[8:11], v[196:199], v[244:247], v[8:11]
	s_setprio 0
	s_setprio 1
	v_mfma_f32_16x16x32_bf16 v[52:55], v[200:203], v[216:219], v[52:55]
	v_mfma_f32_16x16x32_bf16 v[48:51], v[208:211], v[216:219], v[48:51]
	v_mfma_f32_16x16x32_bf16 v[36:39], v[200:203], v[224:227], v[36:39]
	v_mfma_f32_16x16x32_bf16 v[32:35], v[208:211], v[224:227], v[32:35]
	v_mfma_f32_16x16x32_bf16 v[20:23], v[200:203], v[232:235], v[20:23]
	v_mfma_f32_16x16x32_bf16 v[16:19], v[208:211], v[232:235], v[16:19]
	v_mfma_f32_16x16x32_bf16 v[4:7], v[200:203], v[240:243], v[4:7]
	v_mfma_f32_16x16x32_bf16 v[0:3], v[208:211], v[240:243], v[0:3]
	v_mfma_f32_16x16x32_bf16 v[52:55], v[204:207], v[220:223], v[52:55]
	v_mfma_f32_16x16x32_bf16 v[48:51], v[212:215], v[220:223], v[48:51]
	v_mfma_f32_16x16x32_bf16 v[36:39], v[204:207], v[228:231], v[36:39]
	v_mfma_f32_16x16x32_bf16 v[32:35], v[212:215], v[228:231], v[32:35]
	v_mfma_f32_16x16x32_bf16 v[20:23], v[204:207], v[236:239], v[20:23]
	v_mfma_f32_16x16x32_bf16 v[16:19], v[212:215], v[236:239], v[16:19]
	v_mfma_f32_16x16x32_bf16 v[4:7], v[204:207], v[244:247], v[4:7]
	v_mfma_f32_16x16x32_bf16 v[0:3], v[212:215], v[244:247], v[0:3]
	s_setprio 0
	s_barrier
; #define PG8_STAGE(bufoff, gbase, voff) do { _Pragma("unroll") for (int _i = 0; _i < 2; ++_i) \
;         __builtin_amdgcn_global_load_lds((const unsigned*)((const char*)(gbase) + (voff)[_i]), (PG8_LAS unsigned*)(lds + (bufoff) + ldsw + _i * 8192), 16, 0, 0); } while (0)
; #define PG8_LDA(dst, b, h) do { _Pragma("unroll") for (int m = 0; m < 4; ++m) _Pragma("unroll") for (int k = 0; k < 2; ++k) dst[m][k] = *(const PG8_LAS bf16x8*)(lds + PG8_SA(b, h) + aoff + m * 2048 + k * 1024); } while (0)
; #define PG8_LDB(dst, b, h) do { _Pragma("unroll") for (int n = 0; n < 2; ++n) _Pragma("unroll") for (int k = 0; k < 2; ++k) dst[n][k] = *(const PG8_LAS bf16x8*)(lds + PG8_SB(b, h) + boff + n * 2048 + k * 1024); } while (0)
; #define PG8_MMA(ai, bj, At, Bt) do { __builtin_amdgcn_s_setprio(1); _Pragma("unroll") for (int m = 0; m < 4; ++m) _Pragma("unroll") for (int n = 0; n < 2; ++n) _Pragma("unroll") for (int k = 0; k < 2; ++k) \
;         acc[ai][bj][m][n] = __builtin_amdgcn_mfma_f32_16x16x32_bf16(Bt[n][k], At[m][k], acc[ai][bj][m][n], 0, 0, 0); __builtin_amdgcn_s_setprio(0); } while (0)
; #define PG8_WAIT_V(n) asm volatile("s_waitcnt vmcnt(" #n ")" ::: "memory")
; #define PG8_WAIT_L(n) asm volatile("s_waitcnt lgkmcnt(" #n ")" ::: "memory")
; #define PG8_BAR __builtin_amdgcn_s_barrier()
; #define PG8_SCHED __builtin_amdgcn_sched_barrier(0)
; template <class Epi, class Sched, bool ALIGN_EPI = false, bool SP2 = false>
; __device__ __forceinline__ void gemm_phase(PG8_LAS unsigned char* lds, const Gemm g, const Sched& S, const Epi& E) {
;     ...
;             PG8_LDB(B0, 1, 0); PG8_LDB(B1, 1, 1); PG8_SCHED; PG8_LDA(At, 1, 0); PG8_STAGE(PG8_SA(0, 1), a2 + hstep, voffA);
;             PG8_WAIT_V(8); PG8_WAIT_L(0); PG8_BAR; PG8_MMA(0, 0, At, B0); PG8_MMA(0, 1, At, B1); PG8_BAR; PG8_SCHED;
;             PG8_LDA(At, 1, 1); PG8_STAGE(PG8_SB(1, 0), b3, voffB); PG8_STAGE(PG8_SB(1, 1), b3 + hstep, voffB); PG8_STAGE(PG8_SA(1, 0), a3, voffA);
;             PG8_WAIT_V(8); PG8_WAIT_L(0); PG8_BAR; PG8_MMA(1, 0, At, B0); PG8_MMA(1, 1, At, B1); PG8_BAR; PG8_SCHED;
	s_add_i32 s70, 0, 0x18000
	v_add_u32_e32 v177, s70, v174
	s_add_i32 s71, 0, 0x1c000
	ds_read_b128 v[178:181], v177
	ds_read_b128 v[188:191], v177 offset:1024
	ds_read_b128 v[192:195], v177 offset:2048
	ds_read_b128 v[196:199], v177 offset:3072
	v_add_u32_e32 v177, s71, v174
	ds_read_b128 v[200:203], v177
	ds_read_b128 v[204:207], v177 offset:1024
	ds_read_b128 v[208:211], v177 offset:2048
	ds_read_b128 v[212:215], v177 offset:3072
	s_add_u32 s52, s52, 0x80000
	s_addc_u32 s53, s53, 0
	s_mov_b32 m0, s58
	ds_read_b128 v[216:219], v176 offset:32768
	ds_read_b128 v[220:223], v176 offset:33792
	ds_read_b128 v[224:227], v176 offset:34816
	ds_read_b128 v[228:231], v176 offset:35840
	ds_read_b128 v[232:235], v176 offset:36864
	ds_read_b128 v[236:239], v176 offset:37888
	ds_read_b128 v[240:243], v176 offset:38912
	ds_read_b128 v[244:247], v176 offset:39936
	global_load_lds_dwordx4 v128, s[52:53]
	s_mov_b32 m0, s59
	s_nop 0
	global_load_lds_dwordx4 v132, s[52:53]
	s_waitcnt vmcnt(8)
	s_waitcnt lgkmcnt(0)
	s_barrier
	s_setprio 1
	s_waitcnt lgkmcnt(0)
	v_mfma_f32_16x16x32_bf16 v[124:127], v[178:181], v[216:219], v[124:127]
	v_mfma_f32_16x16x32_bf16 v[120:123], v[192:195], v[216:219], v[120:123]
	v_mfma_f32_16x16x32_bf16 v[108:111], v[178:181], v[224:227], v[108:111]
	v_mfma_f32_16x16x32_bf16 v[104:107], v[192:195], v[224:227], v[104:107]
	v_mfma_f32_16x16x32_bf16 v[92:95], v[178:181], v[232:235], v[92:95]
	v_mfma_f32_16x16x32_bf16 v[88:91], v[192:195], v[232:235], v[88:91]
	v_mfma_f32_16x16x32_bf16 v[76:79], v[178:181], v[240:243], v[76:79]
	v_mfma_f32_16x16x32_bf16 v[72:75], v[192:195], v[240:243], v[72:75]
	v_mfma_f32_16x16x32_bf16 v[124:127], v[188:191], v[220:223], v[124:127]
	v_mfma_f32_16x16x32_bf16 v[120:123], v[196:199], v[220:223], v[120:123]
	v_mfma_f32_16x16x32_bf16 v[108:111], v[188:191], v[228:231], v[108:111]
	v_mfma_f32_16x16x32_bf16 v[104:107], v[196:199], v[228:231], v[104:107]
	v_mfma_f32_16x16x32_bf16 v[92:95], v[188:191], v[236:239], v[92:95]
	v_mfma_f32_16x16x32_bf16 v[88:91], v[196:199], v[236:239], v[88:91]
	v_mfma_f32_16x16x32_bf16 v[76:79], v[188:191], v[244:247], v[76:79]
	v_mfma_f32_16x16x32_bf16 v[72:75], v[196:199], v[244:247], v[72:75]
	s_setprio 0
	s_setprio 1
	v_mfma_f32_16x16x32_bf16 v[116:119], v[200:203], v[216:219], v[116:119]
	v_mfma_f32_16x16x32_bf16 v[112:115], v[208:211], v[216:219], v[112:115]
	v_mfma_f32_16x16x32_bf16 v[100:103], v[200:203], v[224:227], v[100:103]
	v_mfma_f32_16x16x32_bf16 v[96:99], v[208:211], v[224:227], v[96:99]
	v_mfma_f32_16x16x32_bf16 v[84:87], v[200:203], v[232:235], v[84:87]
	v_mfma_f32_16x16x32_bf16 v[80:83], v[208:211], v[232:235], v[80:83]
	v_mfma_f32_16x16x32_bf16 v[68:71], v[200:203], v[240:243], v[68:71]
	v_mfma_f32_16x16x32_bf16 v[64:67], v[208:211], v[240:243], v[64:67]
	v_mfma_f32_16x16x32_bf16 v[116:119], v[204:207], v[220:223], v[116:119]
	v_mfma_f32_16x16x32_bf16 v[112:115], v[212:215], v[220:223], v[112:115]
	v_mfma_f32_16x16x32_bf16 v[100:103], v[204:207], v[228:231], v[100:103]
	v_mfma_f32_16x16x32_bf16 v[96:99], v[212:215], v[228:231], v[96:99]
	v_mfma_f32_16x16x32_bf16 v[84:87], v[204:207], v[236:239], v[84:87]
	v_mfma_f32_16x16x32_bf16 v[80:83], v[212:215], v[236:239], v[80:83]
	v_mfma_f32_16x16x32_bf16 v[68:71], v[204:207], v[244:247], v[68:71]
	v_mfma_f32_16x16x32_bf16 v[64:67], v[212:215], v[244:247], v[64:67]
	s_setprio 0
	s_barrier
	s_add_i32 s52, s70, s55
	s_mov_b32 m0, s52
	ds_read_b128 v[216:219], v176 offset:49152
	ds_read_b128 v[220:223], v176 offset:50176
	ds_read_b128 v[224:227], v176 offset:51200
	ds_read_b128 v[228:231], v176 offset:52224
	ds_read_b128 v[232:235], v176 offset:53248
	ds_read_b128 v[236:239], v176 offset:54272
	ds_read_b128 v[240:243], v176 offset:55296
	ds_read_b128 v[244:247], v176 offset:56320
	global_load_lds_dwordx4 v130, s[98:99]
	s_add_i32 m0, s52, 0x2000
	s_add_u32 s50, s50, 0x80080
	s_addc_u32 s51, s51, 0
	s_add_i32 s52, s71, s55
	global_load_lds_dwordx4 v134, s[98:99]
	s_mov_b32 m0, s52
	s_nop 0
	global_load_lds_dwordx4 v130, s[50:51]
	s_add_i32 m0, s52, 0x2000
	s_nop 0
	global_load_lds_dwordx4 v134, s[50:51]
	s_mov_b32 m0, s60
	s_nop 0
	global_load_lds_dwordx4 v128, s[100:101]
	s_mov_b32 m0, s61
	s_nop 0
	global_load_lds_dwordx4 v132, s[100:101]
	s_waitcnt vmcnt(8)
	s_waitcnt lgkmcnt(0)
	s_barrier
	s_setprio 1
	s_waitcnt lgkmcnt(0)
	v_mfma_f32_16x16x32_bf16 v[60:63], v[178:181], v[216:219], v[60:63]
	v_mfma_f32_16x16x32_bf16 v[56:59], v[192:195], v[216:219], v[56:59]
	v_mfma_f32_16x16x32_bf16 v[44:47], v[178:181], v[224:227], v[44:47]
	v_mfma_f32_16x16x32_bf16 v[40:43], v[192:195], v[224:227], v[40:43]
	v_mfma_f32_16x16x32_bf16 v[28:31], v[178:181], v[232:235], v[28:31]
	v_mfma_f32_16x16x32_bf16 v[24:27], v[192:195], v[232:235], v[24:27]
	v_mfma_f32_16x16x32_bf16 v[12:15], v[178:181], v[240:243], v[12:15]
	v_mfma_f32_16x16x32_bf16 v[8:11], v[192:195], v[240:243], v[8:11]
	v_mfma_f32_16x16x32_bf16 v[60:63], v[188:191], v[220:223], v[60:63]
	v_mfma_f32_16x16x32_bf16 v[56:59], v[196:199], v[220:223], v[56:59]
	v_mfma_f32_16x16x32_bf16 v[44:47], v[188:191], v[228:231], v[44:47]
	v_mfma_f32_16x16x32_bf16 v[40:43], v[196:199], v[228:231], v[40:43]
	v_mfma_f32_16x16x32_bf16 v[28:31], v[188:191], v[236:239], v[28:31]
	v_mfma_f32_16x16x32_bf16 v[24:27], v[196:199], v[236:239], v[24:27]
	v_mfma_f32_16x16x32_bf16 v[12:15], v[188:191], v[244:247], v[12:15]
	v_mfma_f32_16x16x32_bf16 v[8:11], v[196:199], v[244:247], v[8:11]
	s_setprio 0
	s_setprio 1
	v_mfma_f32_16x16x32_bf16 v[52:55], v[200:203], v[216:219], v[52:55]
	v_mfma_f32_16x16x32_bf16 v[48:51], v[208:211], v[216:219], v[48:51]
	v_mfma_f32_16x16x32_bf16 v[36:39], v[200:203], v[224:227], v[36:39]
	v_mfma_f32_16x16x32_bf16 v[32:35], v[208:211], v[224:227], v[32:35]
	v_mfma_f32_16x16x32_bf16 v[20:23], v[200:203], v[232:235], v[20:23]
	v_mfma_f32_16x16x32_bf16 v[16:19], v[208:211], v[232:235], v[16:19]
	v_mfma_f32_16x16x32_bf16 v[4:7], v[200:203], v[240:243], v[4:7]
	v_mfma_f32_16x16x32_bf16 v[0:3], v[208:211], v[240:243], v[0:3]
	v_mfma_f32_16x16x32_bf16 v[52:55], v[204:207], v[220:223], v[52:55]
	v_mfma_f32_16x16x32_bf16 v[48:51], v[212:215], v[220:223], v[48:51]
	v_mfma_f32_16x16x32_bf16 v[36:39], v[204:207], v[228:231], v[36:39]
	v_mfma_f32_16x16x32_bf16 v[32:35], v[212:215], v[228:231], v[32:35]
	v_mfma_f32_16x16x32_bf16 v[20:23], v[204:207], v[236:239], v[20:23]
	v_mfma_f32_16x16x32_bf16 v[16:19], v[212:215], v[236:239], v[16:19]
	v_mfma_f32_16x16x32_bf16 v[4:7], v[204:207], v[244:247], v[4:7]
	v_mfma_f32_16x16x32_bf16 v[0:3], v[212:215], v[244:247], v[0:3]
	s_setprio 0
	s_barrier
	s_add_i32 s69, s69, 2
	s_add_u32 s48, s48, 0x100
	s_addc_u32 s49, s49, 0
	s_add_u32 s47, s47, 0x100
	s_addc_u32 s68, s68, 0
	s_cmp_gt_u32 s69, 29
	s_cbranch_scc0 .LBB0_319
	s_and_b64 vcc, exec, s[34:35]
	s_cbranch_vccz .LBB0_343
	s_barrier
	s_cmp_gt_i32 s44, 63
	s_mov_b64 s[50:51], -1
	s_cbranch_scc1 .LBB0_344

; #define PG8_STAGE(bufoff, gbase, voff) do { _Pragma("unroll") for (int _i = 0; _i < 2; ++_i) \
;         __builtin_amdgcn_global_load_lds((const unsigned*)((const char*)(gbase) + (voff)[_i]), (PG8_LAS unsigned*)(lds + (bufoff) + ldsw + _i * 8192), 16, 0, 0); } while (0)
; #define PG8_LDA(dst, b, h) do { _Pragma("unroll") for (int m = 0; m < 4; ++m) _Pragma("unroll") for (int k = 0; k < 2; ++k) dst[m][k] = *(const PG8_LAS bf16x8*)(lds + PG8_SA(b, h) + aoff + m * 2048 + k * 1024); } while (0)
; #define PG8_LDB(dst, b, h) do { _Pragma("unroll") for (int n = 0; n < 2; ++n) _Pragma("unroll") for (int k = 0; k < 2; ++k) dst[n][k] = *(const PG8_LAS bf16x8*)(lds + PG8_SB(b, h) + boff + n * 2048 + k * 1024); } while (0)
; #define PG8_MMA(ai, bj, At, Bt) do { __builtin_amdgcn_s_setprio(1); _Pragma("unroll") for (int m = 0; m < 4; ++m) _Pragma("unroll") for (int n = 0; n < 2; ++n) _Pragma("unroll") for (int k = 0; k < 2; ++k) \
;         acc[ai][bj][m][n] = __builtin_amdgcn_mfma_f32_16x16x32_bf16(Bt[n][k], At[m][k], acc[ai][bj][m][n], 0, 0, 0); __builtin_amdgcn_s_setprio(0); } while (0)
; #define PG8_WAIT_V(n) asm volatile("s_waitcnt vmcnt(" #n ")" ::: "memory")
; #define PG8_WAIT_L(n) asm volatile("s_waitcnt lgkmcnt(" #n ")" ::: "memory")
; #define PG8_BAR __builtin_amdgcn_s_barrier()
; #define PG8_SCHED __builtin_amdgcn_sched_barrier(0)
; template <class Epi, class Sched, bool ALIGN_EPI = false, bool SP2 = false>
; __device__ __forceinline__ void gemm_phase(PG8_LAS unsigned char* lds, const Gemm g, const Sched& S, const Epi& E) {
;     ...
;             const char* a2 = last ? nA : cA + (size_t)(t + 2) * kstep; const char* b2 = last ? nB : cB + (size_t)(t + 2) * kstep;
;             const char* a3 = a2 + kstep; const char* b3 = b2 + kstep;
;             if (last && has_next) S.a_ready(nxt);
;             if constexpr (SP2) {
;             PG8_LDB(B0, 0, 0); PG8_LDB(B1, 0, 1); PG8_SCHED; PG8_LDA(At, 0, 0); PG8_STAGE(PG8_SA(1, 1), a1 + hstep, voffA);
;             PG8_WAIT_V(8); PG8_WAIT_L(0); PG8_BAR; PG8_MMA(0, 0, At, B0); PG8_MMA(0, 1, At, B1); PG8_BAR; PG8_SCHED;
;             PG8_LDA(At, 0, 1); PG8_STAGE(PG8_SB(0, 0), b2, voffB); PG8_STAGE(PG8_SB(0, 1), b2 + hstep, voffB); PG8_STAGE(PG8_SA(0, 0), a2, voffA);
;             PG8_WAIT_V(8); PG8_WAIT_L(0); PG8_BAR; PG8_MMA(1, 0, At, B0); PG8_MMA(1, 1, At, B1); PG8_BAR; PG8_SCHED;
.LBB0_407:
	ds_read_b128 v[144:147], v182
	ds_read_b128 v[148:151], v182 offset:1024
	ds_read_b128 v[152:155], v182 offset:2048
	ds_read_b128 v[156:159], v182 offset:3072
	ds_read_b128 v[160:163], v183
	ds_read_b128 v[168:171], v183 offset:1024
	ds_read_b128 v[172:175], v183 offset:2048
	ds_read_b128 v[190:193], v183 offset:3072
	s_add_u32 s66, s64, 0xfff80080
	s_addc_u32 s67, s65, -1
	s_cmp_eq_u32 s93, 28
	s_cselect_b32 s69, s57, s67
	s_cselect_b32 s68, s89, s66
	s_cselect_b32 s67, s55, s92
	s_cselect_b32 s66, s90, s91
	s_add_i32 m0, s77, 0xc000
	ds_read_b128 v[194:197], v188
	ds_read_b128 v[198:201], v188 offset:1024
	ds_read_b128 v[202:205], v188 offset:2048
	ds_read_b128 v[206:209], v188 offset:3072
	ds_read_b128 v[210:213], v188 offset:4096
	ds_read_b128 v[214:217], v188 offset:5120
	ds_read_b128 v[218:221], v188 offset:6144
	ds_read_b128 v[222:225], v188 offset:7168
	global_load_lds_dwordx4 v136, s[64:65]
	s_add_i32 m0, s77, 0xe000
	s_nop 0
	global_load_lds_dwordx4 v138, s[64:65]
	s_waitcnt vmcnt(8)
	s_waitcnt lgkmcnt(0)
	s_barrier
	s_setprio 1
	s_waitcnt lgkmcnt(0)
	v_mfma_f32_16x16x32_bf16 v[116:119], v[144:147], v[194:197], v[116:119]
	v_mfma_f32_16x16x32_bf16 v[88:91], v[152:155], v[194:197], v[88:91]
	v_mfma_f32_16x16x32_bf16 v[124:127], v[144:147], v[202:205], v[124:127]
	v_mfma_f32_16x16x32_bf16 v[92:95], v[152:155], v[202:205], v[92:95]
	v_mfma_f32_16x16x32_bf16 v[120:123], v[144:147], v[210:213], v[120:123]
	v_mfma_f32_16x16x32_bf16 v[84:87], v[152:155], v[210:213], v[84:87]
	v_mfma_f32_16x16x32_bf16 v[112:115], v[144:147], v[218:221], v[112:115]
	v_mfma_f32_16x16x32_bf16 v[80:83], v[152:155], v[218:221], v[80:83]
	v_mfma_f32_16x16x32_bf16 v[116:119], v[148:151], v[198:201], v[116:119]
	v_mfma_f32_16x16x32_bf16 v[88:91], v[156:159], v[198:201], v[88:91]
	v_mfma_f32_16x16x32_bf16 v[124:127], v[148:151], v[206:209], v[124:127]
	v_mfma_f32_16x16x32_bf16 v[92:95], v[156:159], v[206:209], v[92:95]
	v_mfma_f32_16x16x32_bf16 v[120:123], v[148:151], v[214:217], v[120:123]
	v_mfma_f32_16x16x32_bf16 v[84:87], v[156:159], v[214:217], v[84:87]
	v_mfma_f32_16x16x32_bf16 v[112:115], v[148:151], v[222:225], v[112:115]
	v_mfma_f32_16x16x32_bf16 v[80:83], v[156:159], v[222:225], v[80:83]
	s_setprio 0
	s_setprio 1
	v_mfma_f32_16x16x32_bf16 v[108:111], v[160:163], v[194:197], v[108:111]
	v_mfma_f32_16x16x32_bf16 v[76:79], v[172:175], v[194:197], v[76:79]
	v_mfma_f32_16x16x32_bf16 v[100:103], v[160:163], v[202:205], v[100:103]
	v_mfma_f32_16x16x32_bf16 v[68:71], v[172:175], v[202:205], v[68:71]
	v_mfma_f32_16x16x32_bf16 v[96:99], v[160:163], v[210:213], v[96:99]
	v_mfma_f32_16x16x32_bf16 v[64:67], v[172:175], v[210:213], v[64:67]
	v_mfma_f32_16x16x32_bf16 v[104:107], v[160:163], v[218:221], v[104:107]
	v_mfma_f32_16x16x32_bf16 v[72:75], v[172:175], v[218:221], v[72:75]
	v_mfma_f32_16x16x32_bf16 v[108:111], v[168:171], v[198:201], v[108:111]
	v_mfma_f32_16x16x32_bf16 v[76:79], v[190:193], v[198:201], v[76:79]
	v_mfma_f32_16x16x32_bf16 v[100:103], v[168:171], v[206:209], v[100:103]
	v_mfma_f32_16x16x32_bf16 v[68:71], v[190:193], v[206:209], v[68:71]
	v_mfma_f32_16x16x32_bf16 v[96:99], v[168:171], v[214:217], v[96:99]
	v_mfma_f32_16x16x32_bf16 v[64:67], v[190:193], v[214:217], v[64:67]
	v_mfma_f32_16x16x32_bf16 v[104:107], v[168:171], v[222:225], v[104:107]
	v_mfma_f32_16x16x32_bf16 v[72:75], v[190:193], v[222:225], v[72:75]
	s_setprio 0
	s_barrier
	s_add_u32 s98, s66, 0x80
	s_addc_u32 s99, s67, 0
	s_add_u32 s100, s68, 0x80
	s_addc_u32 s101, s69, 0
	s_add_i32 s94, s85, s75
	s_mov_b32 m0, s94
	ds_read_b128 v[194:197], v188 offset:16384
	ds_read_b128 v[198:201], v188 offset:17408
	ds_read_b128 v[202:205], v188 offset:18432
	ds_read_b128 v[206:209], v188 offset:19456
	ds_read_b128 v[210:213], v188 offset:20480
	ds_read_b128 v[214:217], v188 offset:21504
	ds_read_b128 v[218:221], v188 offset:22528
	ds_read_b128 v[222:225], v188 offset:23552
	global_load_lds_dwordx4 v132, s[66:67]
	s_add_i32 m0, s94, 0x2000
	s_add_u32 s94, s66, 0x80000
	s_addc_u32 s95, s67, 0
	s_add_i32 s96, s86, s75
	global_load_lds_dwordx4 v128, s[66:67]
	s_mov_b32 m0, s96
	s_nop 0
	global_load_lds_dwordx4 v132, s[94:95]
	s_add_i32 m0, s96, 0x2000
	s_nop 0
	global_load_lds_dwordx4 v128, s[94:95]
	s_mov_b32 m0, s77
	s_nop 0
	global_load_lds_dwordx4 v134, s[68:69]
	s_mov_b32 m0, s78
	s_nop 0
	global_load_lds_dwordx4 v130, s[68:69]
	s_waitcnt vmcnt(8)
	s_waitcnt lgkmcnt(0)
	s_barrier
	s_setprio 1
	s_waitcnt lgkmcnt(0)
	v_mfma_f32_16x16x32_bf16 v[56:59], v[144:147], v[194:197], v[56:59]
	v_mfma_f32_16x16x32_bf16 v[24:27], v[152:155], v[194:197], v[24:27]
	v_mfma_f32_16x16x32_bf16 v[60:63], v[144:147], v[202:205], v[60:63]
	v_mfma_f32_16x16x32_bf16 v[28:31], v[152:155], v[202:205], v[28:31]
	v_mfma_f32_16x16x32_bf16 v[52:55], v[144:147], v[210:213], v[52:55]
	v_mfma_f32_16x16x32_bf16 v[20:23], v[152:155], v[210:213], v[20:23]
	v_mfma_f32_16x16x32_bf16 v[48:51], v[144:147], v[218:221], v[48:51]
	v_mfma_f32_16x16x32_bf16 v[16:19], v[152:155], v[218:221], v[16:19]
	v_mfma_f32_16x16x32_bf16 v[56:59], v[148:151], v[198:201], v[56:59]
	v_mfma_f32_16x16x32_bf16 v[24:27], v[156:159], v[198:201], v[24:27]
	v_mfma_f32_16x16x32_bf16 v[60:63], v[148:151], v[206:209], v[60:63]
	v_mfma_f32_16x16x32_bf16 v[28:31], v[156:159], v[206:209], v[28:31]
	v_mfma_f32_16x16x32_bf16 v[52:55], v[148:151], v[214:217], v[52:55]
	v_mfma_f32_16x16x32_bf16 v[20:23], v[156:159], v[214:217], v[20:23]
	v_mfma_f32_16x16x32_bf16 v[48:51], v[148:151], v[222:225], v[48:51]
	v_mfma_f32_16x16x32_bf16 v[16:19], v[156:159], v[222:225], v[16:19]
	s_setprio 0
	s_setprio 1
	v_mfma_f32_16x16x32_bf16 v[44:47], v[160:163], v[194:197], v[44:47]
	v_mfma_f32_16x16x32_bf16 v[12:15], v[172:175], v[194:197], v[12:15]
	v_mfma_f32_16x16x32_bf16 v[36:39], v[160:163], v[202:205], v[36:39]
	v_mfma_f32_16x16x32_bf16 v[4:7], v[172:175], v[202:205], v[4:7]
	v_mfma_f32_16x16x32_bf16 v[32:35], v[160:163], v[210:213], v[32:35]
	v_mfma_f32_16x16x32_bf16 v[0:3], v[172:175], v[210:213], v[0:3]
	v_mfma_f32_16x16x32_bf16 v[40:43], v[160:163], v[218:221], v[40:43]
	v_mfma_f32_16x16x32_bf16 v[8:11], v[172:175], v[218:221], v[8:11]
	v_mfma_f32_16x16x32_bf16 v[44:47], v[168:171], v[198:201], v[44:47]
	v_mfma_f32_16x16x32_bf16 v[12:15], v[190:193], v[198:201], v[12:15]
	v_mfma_f32_16x16x32_bf16 v[36:39], v[168:171], v[206:209], v[36:39]
	v_mfma_f32_16x16x32_bf16 v[4:7], v[190:193], v[206:209], v[4:7]
	v_mfma_f32_16x16x32_bf16 v[32:35], v[168:171], v[214:217], v[32:35]
	v_mfma_f32_16x16x32_bf16 v[0:3], v[190:193], v[214:217], v[0:3]
	v_mfma_f32_16x16x32_bf16 v[40:43], v[168:171], v[222:225], v[40:43]
	v_mfma_f32_16x16x32_bf16 v[8:11], v[190:193], v[222:225], v[8:11]
	s_setprio 0
	s_barrier
; #define PG8_STAGE(bufoff, gbase, voff) do { _Pragma("unroll") for (int _i = 0; _i < 2; ++_i) \
;         __builtin_amdgcn_global_load_lds((const unsigned*)((const char*)(gbase) + (voff)[_i]), (PG8_LAS unsigned*)(lds + (bufoff) + ldsw + _i * 8192), 16, 0, 0); } while (0)
; #define PG8_LDA(dst, b, h) do { _Pragma("unroll") for (int m = 0; m < 4; ++m) _Pragma("unroll") for (int k = 0; k < 2; ++k) dst[m][k] = *(const PG8_LAS bf16x8*)(lds + PG8_SA(b, h) + aoff + m * 2048 + k * 1024); } while (0)
; #define PG8_LDB(dst, b, h) do { _Pragma("unroll") for (int n = 0; n < 2; ++n) _Pragma("unroll") for (int k = 0; k < 2; ++k) dst[n][k] = *(const PG8_LAS bf16x8*)(lds + PG8_SB(b, h) + boff + n * 2048 + k * 1024); } while (0)
; #define PG8_MMA(ai, bj, At, Bt) do { __builtin_amdgcn_s_setprio(1); _Pragma("unroll") for (int m = 0; m < 4; ++m) _Pragma("unroll") for (int n = 0; n < 2; ++n) _Pragma("unroll") for (int k = 0; k < 2; ++k) \
;         acc[ai][bj][m][n] = __builtin_amdgcn_mfma_f32_16x16x32_bf16(Bt[n][k], At[m][k], acc[ai][bj][m][n], 0, 0, 0); __builtin_amdgcn_s_setprio(0); } while (0)
; #define PG8_WAIT_V(n) asm volatile("s_waitcnt vmcnt(" #n ")" ::: "memory")
; #define PG8_WAIT_L(n) asm volatile("s_waitcnt lgkmcnt(" #n ")" ::: "memory")
; #define PG8_BAR __builtin_amdgcn_s_barrier()
; #define PG8_SCHED __builtin_amdgcn_sched_barrier(0)
; template <class Epi, class Sched, bool ALIGN_EPI = false, bool SP2 = false>
; __device__ __forceinline__ void gemm_phase(PG8_LAS unsigned char* lds, const Gemm g, const Sched& S, const Epi& E) {
;     ...
;             PG8_LDB(B0, 1, 0); PG8_LDB(B1, 1, 1); PG8_SCHED; PG8_LDA(At, 1, 0); PG8_STAGE(PG8_SA(0, 1), a2 + hstep, voffA);
;             PG8_WAIT_V(8); PG8_WAIT_L(0); PG8_BAR; PG8_MMA(0, 0, At, B0); PG8_MMA(0, 1, At, B1); PG8_BAR; PG8_SCHED;
;             PG8_LDA(At, 1, 1); PG8_STAGE(PG8_SB(1, 0), b3, voffB); PG8_STAGE(PG8_SB(1, 1), b3 + hstep, voffB); PG8_STAGE(PG8_SA(1, 0), a3, voffA);
;             PG8_WAIT_V(8); PG8_WAIT_L(0); PG8_BAR; PG8_MMA(1, 0, At, B0); PG8_MMA(1, 1, At, B1); PG8_BAR; PG8_SCHED;
	s_add_i32 s94, 0, 0x18000
	s_add_i32 s95, 0, 0x1c000
	v_add_u32_e32 v156, s94, v179
	v_add_u32_e32 v190, s95, v179
	ds_read_b128 v[144:147], v156
	ds_read_b128 v[148:151], v156 offset:1024
	ds_read_b128 v[152:155], v156 offset:2048
	ds_read_b128 v[156:159], v156 offset:3072
	ds_read_b128 v[160:163], v190
	ds_read_b128 v[168:171], v190 offset:1024
	ds_read_b128 v[172:175], v190 offset:2048
	ds_read_b128 v[190:193], v190 offset:3072
	s_add_u32 s68, s68, 0x80000
	s_addc_u32 s69, s69, 0
	s_mov_b32 m0, s79
	ds_read_b128 v[194:197], v188 offset:32768
	ds_read_b128 v[198:201], v188 offset:33792
	ds_read_b128 v[202:205], v188 offset:34816
	ds_read_b128 v[206:209], v188 offset:35840
	ds_read_b128 v[210:213], v188 offset:36864
	ds_read_b128 v[214:217], v188 offset:37888
	ds_read_b128 v[218:221], v188 offset:38912
	ds_read_b128 v[222:225], v188 offset:39936
	global_load_lds_dwordx4 v134, s[68:69]
	s_mov_b32 m0, s80
	s_nop 0
	global_load_lds_dwordx4 v130, s[68:69]
	s_waitcnt vmcnt(8)
	s_waitcnt lgkmcnt(0)
	s_barrier
	s_setprio 1
	s_waitcnt lgkmcnt(0)
	v_mfma_f32_16x16x32_bf16 v[116:119], v[144:147], v[194:197], v[116:119]
	v_mfma_f32_16x16x32_bf16 v[88:91], v[152:155], v[194:197], v[88:91]
	v_mfma_f32_16x16x32_bf16 v[124:127], v[144:147], v[202:205], v[124:127]
	v_mfma_f32_16x16x32_bf16 v[92:95], v[152:155], v[202:205], v[92:95]
	v_mfma_f32_16x16x32_bf16 v[120:123], v[144:147], v[210:213], v[120:123]
	v_mfma_f32_16x16x32_bf16 v[84:87], v[152:155], v[210:213], v[84:87]
	v_mfma_f32_16x16x32_bf16 v[112:115], v[144:147], v[218:221], v[112:115]
	v_mfma_f32_16x16x32_bf16 v[80:83], v[152:155], v[218:221], v[80:83]
	v_mfma_f32_16x16x32_bf16 v[116:119], v[148:151], v[198:201], v[116:119]
	v_mfma_f32_16x16x32_bf16 v[88:91], v[156:159], v[198:201], v[88:91]
	v_mfma_f32_16x16x32_bf16 v[124:127], v[148:151], v[206:209], v[124:127]
	v_mfma_f32_16x16x32_bf16 v[92:95], v[156:159], v[206:209], v[92:95]
	v_mfma_f32_16x16x32_bf16 v[120:123], v[148:151], v[214:217], v[120:123]
	v_mfma_f32_16x16x32_bf16 v[84:87], v[156:159], v[214:217], v[84:87]
	v_mfma_f32_16x16x32_bf16 v[112:115], v[148:151], v[222:225], v[112:115]
	v_mfma_f32_16x16x32_bf16 v[80:83], v[156:159], v[222:225], v[80:83]
	s_setprio 0
	s_setprio 1
	v_mfma_f32_16x16x32_bf16 v[108:111], v[160:163], v[194:197], v[108:111]
	v_mfma_f32_16x16x32_bf16 v[76:79], v[172:175], v[194:197], v[76:79]
	v_mfma_f32_16x16x32_bf16 v[100:103], v[160:163], v[202:205], v[100:103]
	v_mfma_f32_16x16x32_bf16 v[68:71], v[172:175], v[202:205], v[68:71]
	v_mfma_f32_16x16x32_bf16 v[96:99], v[160:163], v[210:213], v[96:99]
	v_mfma_f32_16x16x32_bf16 v[64:67], v[172:175], v[210:213], v[64:67]
	v_mfma_f32_16x16x32_bf16 v[104:107], v[160:163], v[218:221], v[104:107]
	v_mfma_f32_16x16x32_bf16 v[72:75], v[172:175], v[218:221], v[72:75]
	v_mfma_f32_16x16x32_bf16 v[108:111], v[168:171], v[198:201], v[108:111]
	v_mfma_f32_16x16x32_bf16 v[76:79], v[190:193], v[198:201], v[76:79]
	v_mfma_f32_16x16x32_bf16 v[100:103], v[168:171], v[206:209], v[100:103]
	v_mfma_f32_16x16x32_bf16 v[68:71], v[190:193], v[206:209], v[68:71]
	v_mfma_f32_16x16x32_bf16 v[96:99], v[168:171], v[214:217], v[96:99]
	v_mfma_f32_16x16x32_bf16 v[64:67], v[190:193], v[214:217], v[64:67]
	v_mfma_f32_16x16x32_bf16 v[104:107], v[168:171], v[222:225], v[104:107]
	v_mfma_f32_16x16x32_bf16 v[72:75], v[190:193], v[222:225], v[72:75]
	s_setprio 0
	s_barrier
	s_add_i32 s68, s94, s75
	s_mov_b32 m0, s68
	ds_read_b128 v[194:197], v188 offset:49152
	ds_read_b128 v[198:201], v188 offset:50176
	ds_read_b128 v[202:205], v188 offset:51200
	ds_read_b128 v[206:209], v188 offset:52224
	ds_read_b128 v[210:213], v188 offset:53248
	ds_read_b128 v[214:217], v188 offset:54272
	ds_read_b128 v[218:221], v188 offset:55296
	ds_read_b128 v[222:225], v188 offset:56320
	global_load_lds_dwordx4 v132, s[98:99]
	s_add_i32 m0, s68, 0x2000
	s_add_u32 s66, s66, 0x80080
	s_addc_u32 s67, s67, 0
	s_add_i32 s68, s95, s75
	global_load_lds_dwordx4 v128, s[98:99]
	s_mov_b32 m0, s68
	s_nop 0
	global_load_lds_dwordx4 v132, s[66:67]
	s_add_i32 m0, s68, 0x2000
	s_nop 0
	global_load_lds_dwordx4 v128, s[66:67]
	s_mov_b32 m0, s82
	s_nop 0
	global_load_lds_dwordx4 v134, s[100:101]
	s_mov_b32 m0, s83
	s_nop 0
	global_load_lds_dwordx4 v130, s[100:101]
	s_waitcnt vmcnt(8)
	s_waitcnt lgkmcnt(0)
	s_barrier
	s_setprio 1
	s_waitcnt lgkmcnt(0)
	v_mfma_f32_16x16x32_bf16 v[56:59], v[144:147], v[194:197], v[56:59]
	v_mfma_f32_16x16x32_bf16 v[24:27], v[152:155], v[194:197], v[24:27]
	v_mfma_f32_16x16x32_bf16 v[60:63], v[144:147], v[202:205], v[60:63]
	v_mfma_f32_16x16x32_bf16 v[28:31], v[152:155], v[202:205], v[28:31]
	v_mfma_f32_16x16x32_bf16 v[52:55], v[144:147], v[210:213], v[52:55]
	v_mfma_f32_16x16x32_bf16 v[20:23], v[152:155], v[210:213], v[20:23]
	v_mfma_f32_16x16x32_bf16 v[48:51], v[144:147], v[218:221], v[48:51]
	v_mfma_f32_16x16x32_bf16 v[16:19], v[152:155], v[218:221], v[16:19]
	v_mfma_f32_16x16x32_bf16 v[56:59], v[148:151], v[198:201], v[56:59]
	v_mfma_f32_16x16x32_bf16 v[24:27], v[156:159], v[198:201], v[24:27]
	v_mfma_f32_16x16x32_bf16 v[60:63], v[148:151], v[206:209], v[60:63]
	v_mfma_f32_16x16x32_bf16 v[28:31], v[156:159], v[206:209], v[28:31]
	v_mfma_f32_16x16x32_bf16 v[52:55], v[148:151], v[214:217], v[52:55]
	v_mfma_f32_16x16x32_bf16 v[20:23], v[156:159], v[214:217], v[20:23]
	v_mfma_f32_16x16x32_bf16 v[48:51], v[148:151], v[222:225], v[48:51]
	v_mfma_f32_16x16x32_bf16 v[16:19], v[156:159], v[222:225], v[16:19]
	s_setprio 0
	s_setprio 1
	v_mfma_f32_16x16x32_bf16 v[44:47], v[160:163], v[194:197], v[44:47]
	v_mfma_f32_16x16x32_bf16 v[12:15], v[172:175], v[194:197], v[12:15]
	v_mfma_f32_16x16x32_bf16 v[36:39], v[160:163], v[202:205], v[36:39]
	v_mfma_f32_16x16x32_bf16 v[4:7], v[172:175], v[202:205], v[4:7]
	v_mfma_f32_16x16x32_bf16 v[32:35], v[160:163], v[210:213], v[32:35]
	v_mfma_f32_16x16x32_bf16 v[0:3], v[172:175], v[210:213], v[0:3]
	v_mfma_f32_16x16x32_bf16 v[40:43], v[160:163], v[218:221], v[40:43]
	v_mfma_f32_16x16x32_bf16 v[8:11], v[172:175], v[218:221], v[8:11]
	v_mfma_f32_16x16x32_bf16 v[44:47], v[168:171], v[198:201], v[44:47]
	v_mfma_f32_16x16x32_bf16 v[12:15], v[190:193], v[198:201], v[12:15]
	v_mfma_f32_16x16x32_bf16 v[36:39], v[168:171], v[206:209], v[36:39]
	v_mfma_f32_16x16x32_bf16 v[4:7], v[190:193], v[206:209], v[4:7]
	v_mfma_f32_16x16x32_bf16 v[32:35], v[168:171], v[214:217], v[32:35]
	v_mfma_f32_16x16x32_bf16 v[0:3], v[190:193], v[214:217], v[0:3]
	v_mfma_f32_16x16x32_bf16 v[40:43], v[168:171], v[222:225], v[40:43]
	v_mfma_f32_16x16x32_bf16 v[8:11], v[190:193], v[222:225], v[8:11]
	s_setprio 0
	s_barrier
	s_add_i32 s93, s93, 2
	s_add_u32 s64, s64, 0x100
	s_addc_u32 s65, s65, 0
	s_add_u32 s91, s91, 0x100
	s_addc_u32 s92, s92, 0
	s_cmp_gt_u32 s93, 29
	s_cbranch_scc0 .LBB0_407
	s_and_b64 vcc, exec, s[44:45]
	s_cbranch_vccz .LBB0_410
	s_barrier

; #define PG8_STAGE(bufoff, gbase, voff) do { _Pragma("unroll") for (int _i = 0; _i < 2; ++_i) \
;         __builtin_amdgcn_global_load_lds((const unsigned*)((const char*)(gbase) + (voff)[_i]), (PG8_LAS unsigned*)(lds + (bufoff) + ldsw + _i * 8192), 16, 0, 0); } while (0)
; #define PG8_LDA(dst, b, h) do { _Pragma("unroll") for (int m = 0; m < 4; ++m) _Pragma("unroll") for (int k = 0; k < 2; ++k) dst[m][k] = *(const PG8_LAS bf16x8*)(lds + PG8_SA(b, h) + aoff + m * 2048 + k * 1024); } while (0)
; #define PG8_LDB(dst, b, h) do { _Pragma("unroll") for (int n = 0; n < 2; ++n) _Pragma("unroll") for (int k = 0; k < 2; ++k) dst[n][k] = *(const PG8_LAS bf16x8*)(lds + PG8_SB(b, h) + boff + n * 2048 + k * 1024); } while (0)
; #define PG8_MMA(ai, bj, At, Bt) do { __builtin_amdgcn_s_setprio(1); _Pragma("unroll") for (int m = 0; m < 4; ++m) _Pragma("unroll") for (int n = 0; n < 2; ++n) _Pragma("unroll") for (int k = 0; k < 2; ++k) \
;         acc[ai][bj][m][n] = __builtin_amdgcn_mfma_f32_16x16x32_bf16(Bt[n][k], At[m][k], acc[ai][bj][m][n], 0, 0, 0); __builtin_amdgcn_s_setprio(0); } while (0)
; #define PG8_WAIT_V(n) asm volatile("s_waitcnt vmcnt(" #n ")" ::: "memory")
; #define PG8_WAIT_L(n) asm volatile("s_waitcnt lgkmcnt(" #n ")" ::: "memory")
; #define PG8_BAR __builtin_amdgcn_s_barrier()
; #define PG8_SCHED __builtin_amdgcn_sched_barrier(0)
; template <class Epi, class Sched, bool ALIGN_EPI = false, bool SP2 = false>
; __device__ __forceinline__ void gemm_phase(PG8_LAS unsigned char* lds, const Gemm g, const Sched& S, const Epi& E) {
;     ...
;             const char* a2 = last ? nA : cA + (size_t)(t + 2) * kstep; const char* b2 = last ? nB : cB + (size_t)(t + 2) * kstep;
;             const char* a3 = a2 + kstep; const char* b3 = b2 + kstep;
;             if (last && has_next) S.a_ready(nxt);
;             if constexpr (SP2) {
;             PG8_LDB(B0, 0, 0); PG8_LDB(B1, 0, 1); PG8_SCHED; PG8_LDA(At, 0, 0); PG8_STAGE(PG8_SA(1, 1), a1 + hstep, voffA);
;             PG8_WAIT_V(8); PG8_WAIT_L(0); PG8_BAR; PG8_MMA(0, 0, At, B0); PG8_MMA(0, 1, At, B1); PG8_BAR; PG8_SCHED;
;             PG8_LDA(At, 0, 1); PG8_STAGE(PG8_SB(0, 0), b2, voffB); PG8_STAGE(PG8_SB(0, 1), b2 + hstep, voffB); PG8_STAGE(PG8_SA(0, 0), a2, voffA);
;             PG8_WAIT_V(8); PG8_WAIT_L(0); PG8_BAR; PG8_MMA(1, 0, At, B0); PG8_MMA(1, 1, At, B1); PG8_BAR; PG8_SCHED;
.LBB0_560:
	v_add_u32_e32 v189, s67, v168
	ds_read_b128 v[160:163], v170
	ds_read_b128 v[172:175], v170 offset:1024
	ds_read_b128 v[176:179], v170 offset:2048
	ds_read_b128 v[180:183], v170 offset:3072
	ds_read_b128 v[190:193], v189
	ds_read_b128 v[194:197], v189 offset:1024
	ds_read_b128 v[198:201], v189 offset:2048
	ds_read_b128 v[202:205], v189 offset:3072
	s_add_u32 s48, s46, 0x100
	s_addc_u32 s49, s47, 0
	s_cmpk_eq_i32 s75, 0x52
	s_cselect_b32 s53, s13, s49
	s_cselect_b32 s52, s12, s48
	s_cselect_b32 s51, s43, s74
	s_cselect_b32 s50, s42, s45
	s_add_i32 m0, s59, 0xc000
	ds_read_b128 v[206:209], v171
	ds_read_b128 v[210:213], v171 offset:1024
	ds_read_b128 v[214:217], v171 offset:2048
	ds_read_b128 v[218:221], v171 offset:3072
	ds_read_b128 v[222:225], v171 offset:4096
	ds_read_b128 v[226:229], v171 offset:5120
	ds_read_b128 v[230:233], v171 offset:6144
	ds_read_b128 v[234:237], v171 offset:7168
	global_load_lds_dwordx4 v152, s[46:47]
	s_add_i32 m0, s59, 0xe000
	s_nop 0
	global_load_lds_dwordx4 v154, s[46:47]
	s_waitcnt vmcnt(8)
	s_waitcnt lgkmcnt(0)
	s_barrier
	s_setprio 1
	s_waitcnt lgkmcnt(0)
	v_mfma_f32_16x16x32_bf16 v[124:127], v[160:163], v[206:209], v[124:127]
	v_mfma_f32_16x16x32_bf16 v[120:123], v[176:179], v[206:209], v[120:123]
	v_mfma_f32_16x16x32_bf16 v[108:111], v[160:163], v[214:217], v[108:111]
	v_mfma_f32_16x16x32_bf16 v[104:107], v[176:179], v[214:217], v[104:107]
	v_mfma_f32_16x16x32_bf16 v[92:95], v[160:163], v[222:225], v[92:95]
	v_mfma_f32_16x16x32_bf16 v[88:91], v[176:179], v[222:225], v[88:91]
	v_mfma_f32_16x16x32_bf16 v[76:79], v[160:163], v[230:233], v[76:79]
	v_mfma_f32_16x16x32_bf16 v[72:75], v[176:179], v[230:233], v[72:75]
	v_mfma_f32_16x16x32_bf16 v[124:127], v[172:175], v[210:213], v[124:127]
	v_mfma_f32_16x16x32_bf16 v[120:123], v[180:183], v[210:213], v[120:123]
	v_mfma_f32_16x16x32_bf16 v[108:111], v[172:175], v[218:221], v[108:111]
	v_mfma_f32_16x16x32_bf16 v[104:107], v[180:183], v[218:221], v[104:107]
	v_mfma_f32_16x16x32_bf16 v[92:95], v[172:175], v[226:229], v[92:95]
	v_mfma_f32_16x16x32_bf16 v[88:91], v[180:183], v[226:229], v[88:91]
	v_mfma_f32_16x16x32_bf16 v[76:79], v[172:175], v[234:237], v[76:79]
	v_mfma_f32_16x16x32_bf16 v[72:75], v[180:183], v[234:237], v[72:75]
	s_setprio 0
	s_setprio 1
	v_mfma_f32_16x16x32_bf16 v[116:119], v[190:193], v[206:209], v[116:119]
	v_mfma_f32_16x16x32_bf16 v[112:115], v[198:201], v[206:209], v[112:115]
	v_mfma_f32_16x16x32_bf16 v[100:103], v[190:193], v[214:217], v[100:103]
	v_mfma_f32_16x16x32_bf16 v[96:99], v[198:201], v[214:217], v[96:99]
	v_mfma_f32_16x16x32_bf16 v[84:87], v[190:193], v[222:225], v[84:87]
	v_mfma_f32_16x16x32_bf16 v[80:83], v[198:201], v[222:225], v[80:83]
	v_mfma_f32_16x16x32_bf16 v[68:71], v[190:193], v[230:233], v[68:71]
	v_mfma_f32_16x16x32_bf16 v[64:67], v[198:201], v[230:233], v[64:67]
	v_mfma_f32_16x16x32_bf16 v[116:119], v[194:197], v[210:213], v[116:119]
	v_mfma_f32_16x16x32_bf16 v[112:115], v[202:205], v[210:213], v[112:115]
	v_mfma_f32_16x16x32_bf16 v[100:103], v[194:197], v[218:221], v[100:103]
	v_mfma_f32_16x16x32_bf16 v[96:99], v[202:205], v[218:221], v[96:99]
	v_mfma_f32_16x16x32_bf16 v[84:87], v[194:197], v[226:229], v[84:87]
	v_mfma_f32_16x16x32_bf16 v[80:83], v[202:205], v[226:229], v[80:83]
	v_mfma_f32_16x16x32_bf16 v[68:71], v[194:197], v[234:237], v[68:71]
	v_mfma_f32_16x16x32_bf16 v[64:67], v[202:205], v[234:237], v[64:67]
	s_setprio 0
	s_barrier
	s_add_u32 s98, s50, 0x80
	s_addc_u32 s99, s51, 0
	s_add_u32 s100, s52, 0x80
	s_addc_u32 s101, s53, 0
	s_add_i32 s46, s66, s58
	s_mov_b32 m0, s46
	ds_read_b128 v[206:209], v171 offset:16384
	ds_read_b128 v[210:213], v171 offset:17408
	ds_read_b128 v[214:217], v171 offset:18432
	ds_read_b128 v[218:221], v171 offset:19456
	ds_read_b128 v[222:225], v171 offset:20480
	ds_read_b128 v[226:229], v171 offset:21504
	ds_read_b128 v[230:233], v171 offset:22528
	ds_read_b128 v[234:237], v171 offset:23552
	global_load_lds_dwordx4 v130, s[50:51]
	s_add_i32 m0, s46, 0x2000
	s_add_u32 s46, s50, 0x158000
	s_addc_u32 s47, s51, 0
	s_add_i32 s76, s67, s58
	global_load_lds_dwordx4 v134, s[50:51]
	s_mov_b32 m0, s76
	s_nop 0
	global_load_lds_dwordx4 v130, s[46:47]
	s_add_i32 m0, s76, 0x2000
	s_nop 0
	global_load_lds_dwordx4 v134, s[46:47]
	s_mov_b32 m0, s59
	s_nop 0
	global_load_lds_dwordx4 v128, s[52:53]
	s_mov_b32 m0, s60
	s_nop 0
	global_load_lds_dwordx4 v132, s[52:53]
	s_waitcnt vmcnt(8)
	s_waitcnt lgkmcnt(0)
	s_barrier
	s_setprio 1
	s_waitcnt lgkmcnt(0)
	v_mfma_f32_16x16x32_bf16 v[60:63], v[160:163], v[206:209], v[60:63]
	v_mfma_f32_16x16x32_bf16 v[56:59], v[176:179], v[206:209], v[56:59]
	v_mfma_f32_16x16x32_bf16 v[44:47], v[160:163], v[214:217], v[44:47]
	v_mfma_f32_16x16x32_bf16 v[40:43], v[176:179], v[214:217], v[40:43]
	v_mfma_f32_16x16x32_bf16 v[28:31], v[160:163], v[222:225], v[28:31]
	v_mfma_f32_16x16x32_bf16 v[24:27], v[176:179], v[222:225], v[24:27]
	v_mfma_f32_16x16x32_bf16 v[12:15], v[160:163], v[230:233], v[12:15]
	v_mfma_f32_16x16x32_bf16 v[8:11], v[176:179], v[230:233], v[8:11]
	v_mfma_f32_16x16x32_bf16 v[60:63], v[172:175], v[210:213], v[60:63]
	v_mfma_f32_16x16x32_bf16 v[56:59], v[180:183], v[210:213], v[56:59]
	v_mfma_f32_16x16x32_bf16 v[44:47], v[172:175], v[218:221], v[44:47]
	v_mfma_f32_16x16x32_bf16 v[40:43], v[180:183], v[218:221], v[40:43]
	v_mfma_f32_16x16x32_bf16 v[28:31], v[172:175], v[226:229], v[28:31]
	v_mfma_f32_16x16x32_bf16 v[24:27], v[180:183], v[226:229], v[24:27]
	v_mfma_f32_16x16x32_bf16 v[12:15], v[172:175], v[234:237], v[12:15]
	v_mfma_f32_16x16x32_bf16 v[8:11], v[180:183], v[234:237], v[8:11]
	s_setprio 0
	s_setprio 1
	v_mfma_f32_16x16x32_bf16 v[52:55], v[190:193], v[206:209], v[52:55]
	v_mfma_f32_16x16x32_bf16 v[48:51], v[198:201], v[206:209], v[48:51]
	v_mfma_f32_16x16x32_bf16 v[36:39], v[190:193], v[214:217], v[36:39]
	v_mfma_f32_16x16x32_bf16 v[32:35], v[198:201], v[214:217], v[32:35]
	v_mfma_f32_16x16x32_bf16 v[20:23], v[190:193], v[222:225], v[20:23]
	v_mfma_f32_16x16x32_bf16 v[16:19], v[198:201], v[222:225], v[16:19]
	v_mfma_f32_16x16x32_bf16 v[4:7], v[190:193], v[230:233], v[4:7]
	v_mfma_f32_16x16x32_bf16 v[0:3], v[198:201], v[230:233], v[0:3]
	v_mfma_f32_16x16x32_bf16 v[52:55], v[194:197], v[210:213], v[52:55]
	v_mfma_f32_16x16x32_bf16 v[48:51], v[202:205], v[210:213], v[48:51]
	v_mfma_f32_16x16x32_bf16 v[36:39], v[194:197], v[218:221], v[36:39]
	v_mfma_f32_16x16x32_bf16 v[32:35], v[202:205], v[218:221], v[32:35]
	v_mfma_f32_16x16x32_bf16 v[20:23], v[194:197], v[226:229], v[20:23]
	v_mfma_f32_16x16x32_bf16 v[16:19], v[202:205], v[226:229], v[16:19]
	v_mfma_f32_16x16x32_bf16 v[4:7], v[194:197], v[234:237], v[4:7]
	v_mfma_f32_16x16x32_bf16 v[0:3], v[202:205], v[234:237], v[0:3]
	s_setprio 0
	s_barrier
; #define PG8_STAGE(bufoff, gbase, voff) do { _Pragma("unroll") for (int _i = 0; _i < 2; ++_i) \
;         __builtin_amdgcn_global_load_lds((const unsigned*)((const char*)(gbase) + (voff)[_i]), (PG8_LAS unsigned*)(lds + (bufoff) + ldsw + _i * 8192), 16, 0, 0); } while (0)
; #define PG8_LDA(dst, b, h) do { _Pragma("unroll") for (int m = 0; m < 4; ++m) _Pragma("unroll") for (int k = 0; k < 2; ++k) dst[m][k] = *(const PG8_LAS bf16x8*)(lds + PG8_SA(b, h) + aoff + m * 2048 + k * 1024); } while (0)
; #define PG8_LDB(dst, b, h) do { _Pragma("unroll") for (int n = 0; n < 2; ++n) _Pragma("unroll") for (int k = 0; k < 2; ++k) dst[n][k] = *(const PG8_LAS bf16x8*)(lds + PG8_SB(b, h) + boff + n * 2048 + k * 1024); } while (0)
; #define PG8_MMA(ai, bj, At, Bt) do { __builtin_amdgcn_s_setprio(1); _Pragma("unroll") for (int m = 0; m < 4; ++m) _Pragma("unroll") for (int n = 0; n < 2; ++n) _Pragma("unroll") for (int k = 0; k < 2; ++k) \
;         acc[ai][bj][m][n] = __builtin_amdgcn_mfma_f32_16x16x32_bf16(Bt[n][k], At[m][k], acc[ai][bj][m][n], 0, 0, 0); __builtin_amdgcn_s_setprio(0); } while (0)
; #define PG8_WAIT_V(n) asm volatile("s_waitcnt vmcnt(" #n ")" ::: "memory")
; #define PG8_WAIT_L(n) asm volatile("s_waitcnt lgkmcnt(" #n ")" ::: "memory")
; #define PG8_BAR __builtin_amdgcn_s_barrier()
; #define PG8_SCHED __builtin_amdgcn_sched_barrier(0)
; template <class Epi, class Sched, bool ALIGN_EPI = false, bool SP2 = false>
; __device__ __forceinline__ void gemm_phase(PG8_LAS unsigned char* lds, const Gemm g, const Sched& S, const Epi& E) {
;     ...
;             PG8_LDB(B0, 1, 0); PG8_LDB(B1, 1, 1); PG8_SCHED; PG8_LDA(At, 1, 0); PG8_STAGE(PG8_SA(0, 1), a2 + hstep, voffA);
;             PG8_WAIT_V(8); PG8_WAIT_L(0); PG8_BAR; PG8_MMA(0, 0, At, B0); PG8_MMA(0, 1, At, B1); PG8_BAR; PG8_SCHED;
;             PG8_LDA(At, 1, 1); PG8_STAGE(PG8_SB(1, 0), b3, voffB); PG8_STAGE(PG8_SB(1, 1), b3 + hstep, voffB); PG8_STAGE(PG8_SA(1, 0), a3, voffA);
;             PG8_WAIT_V(8); PG8_WAIT_L(0); PG8_BAR; PG8_MMA(1, 0, At, B0); PG8_MMA(1, 1, At, B1); PG8_BAR; PG8_SCHED;
	s_add_i32 s76, 0, 0x18000
	s_add_i32 s77, 0, 0x1c000
	v_add_u32_e32 v180, s76, v168
	v_add_u32_e32 v189, s77, v168
	ds_read_b128 v[160:163], v180
	ds_read_b128 v[172:175], v180 offset:1024
	ds_read_b128 v[176:179], v180 offset:2048
	ds_read_b128 v[180:183], v180 offset:3072
	ds_read_b128 v[190:193], v189
	ds_read_b128 v[194:197], v189 offset:1024
	ds_read_b128 v[198:201], v189 offset:2048
	ds_read_b128 v[202:205], v189 offset:3072
	s_add_u32 s46, s52, 0x158000
	s_addc_u32 s47, s53, 0
	s_mov_b32 m0, s61
	ds_read_b128 v[206:209], v171 offset:32768
	ds_read_b128 v[210:213], v171 offset:33792
	ds_read_b128 v[214:217], v171 offset:34816
	ds_read_b128 v[218:221], v171 offset:35840
	ds_read_b128 v[222:225], v171 offset:36864
	ds_read_b128 v[226:229], v171 offset:37888
	ds_read_b128 v[230:233], v171 offset:38912
	ds_read_b128 v[234:237], v171 offset:39936
	global_load_lds_dwordx4 v128, s[46:47]
	s_mov_b32 m0, s62
	s_nop 0
	global_load_lds_dwordx4 v132, s[46:47]
	s_waitcnt vmcnt(8)
	s_waitcnt lgkmcnt(0)
	s_barrier
	s_setprio 1
	s_waitcnt lgkmcnt(0)
	v_mfma_f32_16x16x32_bf16 v[124:127], v[160:163], v[206:209], v[124:127]
	v_mfma_f32_16x16x32_bf16 v[120:123], v[176:179], v[206:209], v[120:123]
	v_mfma_f32_16x16x32_bf16 v[108:111], v[160:163], v[214:217], v[108:111]
	v_mfma_f32_16x16x32_bf16 v[104:107], v[176:179], v[214:217], v[104:107]
	v_mfma_f32_16x16x32_bf16 v[92:95], v[160:163], v[222:225], v[92:95]
	v_mfma_f32_16x16x32_bf16 v[88:91], v[176:179], v[222:225], v[88:91]
	v_mfma_f32_16x16x32_bf16 v[76:79], v[160:163], v[230:233], v[76:79]
	v_mfma_f32_16x16x32_bf16 v[72:75], v[176:179], v[230:233], v[72:75]
	v_mfma_f32_16x16x32_bf16 v[124:127], v[172:175], v[210:213], v[124:127]
	v_mfma_f32_16x16x32_bf16 v[120:123], v[180:183], v[210:213], v[120:123]
	v_mfma_f32_16x16x32_bf16 v[108:111], v[172:175], v[218:221], v[108:111]
	v_mfma_f32_16x16x32_bf16 v[104:107], v[180:183], v[218:221], v[104:107]
	v_mfma_f32_16x16x32_bf16 v[92:95], v[172:175], v[226:229], v[92:95]
	v_mfma_f32_16x16x32_bf16 v[88:91], v[180:183], v[226:229], v[88:91]
	v_mfma_f32_16x16x32_bf16 v[76:79], v[172:175], v[234:237], v[76:79]
	v_mfma_f32_16x16x32_bf16 v[72:75], v[180:183], v[234:237], v[72:75]
	s_setprio 0
	s_setprio 1
	v_mfma_f32_16x16x32_bf16 v[116:119], v[190:193], v[206:209], v[116:119]
	v_mfma_f32_16x16x32_bf16 v[112:115], v[198:201], v[206:209], v[112:115]
	v_mfma_f32_16x16x32_bf16 v[100:103], v[190:193], v[214:217], v[100:103]
	v_mfma_f32_16x16x32_bf16 v[96:99], v[198:201], v[214:217], v[96:99]
	v_mfma_f32_16x16x32_bf16 v[84:87], v[190:193], v[222:225], v[84:87]
	v_mfma_f32_16x16x32_bf16 v[80:83], v[198:201], v[222:225], v[80:83]
	v_mfma_f32_16x16x32_bf16 v[68:71], v[190:193], v[230:233], v[68:71]
	v_mfma_f32_16x16x32_bf16 v[64:67], v[198:201], v[230:233], v[64:67]
	v_mfma_f32_16x16x32_bf16 v[116:119], v[194:197], v[210:213], v[116:119]
	v_mfma_f32_16x16x32_bf16 v[112:115], v[202:205], v[210:213], v[112:115]
	v_mfma_f32_16x16x32_bf16 v[100:103], v[194:197], v[218:221], v[100:103]
	v_mfma_f32_16x16x32_bf16 v[96:99], v[202:205], v[218:221], v[96:99]
	v_mfma_f32_16x16x32_bf16 v[84:87], v[194:197], v[226:229], v[84:87]
	v_mfma_f32_16x16x32_bf16 v[80:83], v[202:205], v[226:229], v[80:83]
	v_mfma_f32_16x16x32_bf16 v[68:71], v[194:197], v[234:237], v[68:71]
	v_mfma_f32_16x16x32_bf16 v[64:67], v[202:205], v[234:237], v[64:67]
	s_setprio 0
	s_barrier
	s_add_i32 s46, s76, s58
	s_mov_b32 m0, s46
	ds_read_b128 v[206:209], v171 offset:49152
	ds_read_b128 v[210:213], v171 offset:50176
	ds_read_b128 v[214:217], v171 offset:51200
	ds_read_b128 v[218:221], v171 offset:52224
	ds_read_b128 v[222:225], v171 offset:53248
	ds_read_b128 v[226:229], v171 offset:54272
	ds_read_b128 v[230:233], v171 offset:55296
	ds_read_b128 v[234:237], v171 offset:56320
	global_load_lds_dwordx4 v130, s[98:99]
	s_add_i32 m0, s46, 0x2000
	s_add_u32 s46, s50, 0x158080
	s_addc_u32 s47, s51, 0
	s_add_i32 s50, s77, s58
	global_load_lds_dwordx4 v134, s[98:99]
	s_mov_b32 m0, s50
	s_nop 0
	global_load_lds_dwordx4 v130, s[46:47]
	s_add_i32 m0, s50, 0x2000
	s_nop 0
	global_load_lds_dwordx4 v134, s[46:47]
	s_mov_b32 m0, s64
	s_nop 0
	global_load_lds_dwordx4 v128, s[100:101]
	s_mov_b32 m0, s65
	s_nop 0
	global_load_lds_dwordx4 v132, s[100:101]
	s_waitcnt vmcnt(8)
	s_waitcnt lgkmcnt(0)
	s_barrier
	s_setprio 1
	s_waitcnt lgkmcnt(0)
	v_mfma_f32_16x16x32_bf16 v[60:63], v[160:163], v[206:209], v[60:63]
	v_mfma_f32_16x16x32_bf16 v[56:59], v[176:179], v[206:209], v[56:59]
	v_mfma_f32_16x16x32_bf16 v[44:47], v[160:163], v[214:217], v[44:47]
	v_mfma_f32_16x16x32_bf16 v[40:43], v[176:179], v[214:217], v[40:43]
	v_mfma_f32_16x16x32_bf16 v[28:31], v[160:163], v[222:225], v[28:31]
	v_mfma_f32_16x16x32_bf16 v[24:27], v[176:179], v[222:225], v[24:27]
	v_mfma_f32_16x16x32_bf16 v[12:15], v[160:163], v[230:233], v[12:15]
	v_mfma_f32_16x16x32_bf16 v[8:11], v[176:179], v[230:233], v[8:11]
	v_mfma_f32_16x16x32_bf16 v[60:63], v[172:175], v[210:213], v[60:63]
	v_mfma_f32_16x16x32_bf16 v[56:59], v[180:183], v[210:213], v[56:59]
	v_mfma_f32_16x16x32_bf16 v[44:47], v[172:175], v[218:221], v[44:47]
	v_mfma_f32_16x16x32_bf16 v[40:43], v[180:183], v[218:221], v[40:43]
	v_mfma_f32_16x16x32_bf16 v[28:31], v[172:175], v[226:229], v[28:31]
	v_mfma_f32_16x16x32_bf16 v[24:27], v[180:183], v[226:229], v[24:27]
	v_mfma_f32_16x16x32_bf16 v[12:15], v[172:175], v[234:237], v[12:15]
	v_mfma_f32_16x16x32_bf16 v[8:11], v[180:183], v[234:237], v[8:11]
	s_setprio 0
	s_setprio 1
	v_mfma_f32_16x16x32_bf16 v[52:55], v[190:193], v[206:209], v[52:55]
	v_mfma_f32_16x16x32_bf16 v[48:51], v[198:201], v[206:209], v[48:51]
	v_mfma_f32_16x16x32_bf16 v[36:39], v[190:193], v[214:217], v[36:39]
	v_mfma_f32_16x16x32_bf16 v[32:35], v[198:201], v[214:217], v[32:35]
	v_mfma_f32_16x16x32_bf16 v[20:23], v[190:193], v[222:225], v[20:23]
	v_mfma_f32_16x16x32_bf16 v[16:19], v[198:201], v[222:225], v[16:19]
	v_mfma_f32_16x16x32_bf16 v[4:7], v[190:193], v[230:233], v[4:7]
	v_mfma_f32_16x16x32_bf16 v[0:3], v[198:201], v[230:233], v[0:3]
	v_mfma_f32_16x16x32_bf16 v[52:55], v[194:197], v[210:213], v[52:55]
	v_mfma_f32_16x16x32_bf16 v[48:51], v[202:205], v[210:213], v[48:51]
	v_mfma_f32_16x16x32_bf16 v[36:39], v[194:197], v[218:221], v[36:39]
	v_mfma_f32_16x16x32_bf16 v[32:35], v[202:205], v[218:221], v[32:35]
	v_mfma_f32_16x16x32_bf16 v[20:23], v[194:197], v[226:229], v[20:23]
	v_mfma_f32_16x16x32_bf16 v[16:19], v[202:205], v[226:229], v[16:19]
	v_mfma_f32_16x16x32_bf16 v[4:7], v[194:197], v[234:237], v[4:7]
	v_mfma_f32_16x16x32_bf16 v[0:3], v[202:205], v[234:237], v[0:3]
	s_setprio 0
	s_barrier
	s_add_i32 s75, s75, 2
	s_add_u32 s45, s45, 0x100
	s_addc_u32 s74, s74, 0
	s_cmpk_gt_u32 s75, 0x53
	s_mov_b64 s[46:47], s[48:49]
	s_cbranch_scc0 .LBB0_560
	s_and_b64 vcc, exec, s[40:41]
	s_cbranch_vccz .LBB0_563
	s_barrier

; #define PG8_STAGE(bufoff, gbase, voff) do { _Pragma("unroll") for (int _i = 0; _i < 2; ++_i) \
;         __builtin_amdgcn_global_load_lds((const unsigned*)((const char*)(gbase) + (voff)[_i]), (PG8_LAS unsigned*)(lds + (bufoff) + ldsw + _i * 8192), 16, 0, 0); } while (0)
; #define PG8_LDA(dst, b, h) do { _Pragma("unroll") for (int m = 0; m < 4; ++m) _Pragma("unroll") for (int k = 0; k < 2; ++k) dst[m][k] = *(const PG8_LAS bf16x8*)(lds + PG8_SA(b, h) + aoff + m * 2048 + k * 1024); } while (0)
; #define PG8_LDB(dst, b, h) do { _Pragma("unroll") for (int n = 0; n < 2; ++n) _Pragma("unroll") for (int k = 0; k < 2; ++k) dst[n][k] = *(const PG8_LAS bf16x8*)(lds + PG8_SB(b, h) + boff + n * 2048 + k * 1024); } while (0)
; #define PG8_MMA(ai, bj, At, Bt) do { __builtin_amdgcn_s_setprio(1); _Pragma("unroll") for (int m = 0; m < 4; ++m) _Pragma("unroll") for (int n = 0; n < 2; ++n) _Pragma("unroll") for (int k = 0; k < 2; ++k) \
;         acc[ai][bj][m][n] = __builtin_amdgcn_mfma_f32_16x16x32_bf16(Bt[n][k], At[m][k], acc[ai][bj][m][n], 0, 0, 0); __builtin_amdgcn_s_setprio(0); } while (0)
; #define PG8_WAIT_V(n) asm volatile("s_waitcnt vmcnt(" #n ")" ::: "memory")
; #define PG8_WAIT_L(n) asm volatile("s_waitcnt lgkmcnt(" #n ")" ::: "memory")
; #define PG8_BAR __builtin_amdgcn_s_barrier()
; #define PG8_SCHED __builtin_amdgcn_sched_barrier(0)
; template <class Epi, class Sched, bool ALIGN_EPI = false, bool SP2 = false>
; __device__ __forceinline__ void gemm_phase(PG8_LAS unsigned char* lds, const Gemm g, const Sched& S, const Epi& E) {
;     ...
;             const char* a2 = last ? nA : cA + (size_t)(t + 2) * kstep; const char* b2 = last ? nB : cB + (size_t)(t + 2) * kstep;
;             const char* a3 = a2 + kstep; const char* b3 = b2 + kstep;
;             if (last && has_next) S.a_ready(nxt);
;             if constexpr (SP2) {
;             PG8_LDB(B0, 0, 0); PG8_LDB(B1, 0, 1); PG8_SCHED; PG8_LDA(At, 0, 0); PG8_STAGE(PG8_SA(1, 1), a1 + hstep, voffA);
;             PG8_WAIT_V(8); PG8_WAIT_L(0); PG8_BAR; PG8_MMA(0, 0, At, B0); PG8_MMA(0, 1, At, B1); PG8_BAR; PG8_SCHED;
;             PG8_LDA(At, 0, 1); PG8_STAGE(PG8_SB(0, 0), b2, voffB); PG8_STAGE(PG8_SB(0, 1), b2 + hstep, voffB); PG8_STAGE(PG8_SA(0, 0), a2, voffA);
;             PG8_WAIT_V(8); PG8_WAIT_L(0); PG8_BAR; PG8_MMA(1, 0, At, B0); PG8_MMA(1, 1, At, B1); PG8_BAR; PG8_SCHED;
.LBB0_644:
	ds_read_b128 v[144:147], v193
	ds_read_b128 v[148:151], v193 offset:1024
	ds_read_b128 v[152:155], v193 offset:2048
	ds_read_b128 v[156:159], v193 offset:3072
	ds_read_b128 v[160:163], v194
	ds_read_b128 v[168:171], v194 offset:1024
	ds_read_b128 v[172:175], v194 offset:2048
	ds_read_b128 v[176:179], v194 offset:3072
	s_add_u32 s68, s66, 0xfff80080
	s_addc_u32 s69, s67, -1
	s_cmp_eq_u32 s96, 28
	s_cselect_b32 s71, s59, s69
	s_cselect_b32 s70, s92, s68
	s_cselect_b32 s69, s57, s95
	s_cselect_b32 s68, s93, s94
	s_add_i32 m0, s80, 0xc000
	ds_read_b128 v[180:183], v195
	ds_read_b128 v[198:201], v195 offset:1024
	ds_read_b128 v[202:205], v195 offset:2048
	ds_read_b128 v[206:209], v195 offset:3072
	ds_read_b128 v[210:213], v195 offset:4096
	ds_read_b128 v[214:217], v195 offset:5120
	ds_read_b128 v[218:221], v195 offset:6144
	ds_read_b128 v[222:225], v195 offset:7168
	global_load_lds_dwordx4 v138, s[66:67]
	s_add_i32 m0, s80, 0xe000
	s_nop 0
	global_load_lds_dwordx4 v136, s[66:67]
	s_waitcnt vmcnt(8)
	s_waitcnt lgkmcnt(0)
	s_barrier
	s_setprio 1
	s_waitcnt lgkmcnt(0)
	v_mfma_f32_16x16x32_bf16 v[124:127], v[144:147], v[180:183], v[124:127]
	v_mfma_f32_16x16x32_bf16 v[88:91], v[152:155], v[180:183], v[88:91]
	v_mfma_f32_16x16x32_bf16 v[120:123], v[144:147], v[202:205], v[120:123]
	v_mfma_f32_16x16x32_bf16 v[92:95], v[152:155], v[202:205], v[92:95]
	v_mfma_f32_16x16x32_bf16 v[116:119], v[144:147], v[210:213], v[116:119]
	v_mfma_f32_16x16x32_bf16 v[84:87], v[152:155], v[210:213], v[84:87]
	v_mfma_f32_16x16x32_bf16 v[112:115], v[144:147], v[218:221], v[112:115]
	v_mfma_f32_16x16x32_bf16 v[80:83], v[152:155], v[218:221], v[80:83]
	v_mfma_f32_16x16x32_bf16 v[124:127], v[148:151], v[198:201], v[124:127]
	v_mfma_f32_16x16x32_bf16 v[88:91], v[156:159], v[198:201], v[88:91]
	v_mfma_f32_16x16x32_bf16 v[120:123], v[148:151], v[206:209], v[120:123]
	v_mfma_f32_16x16x32_bf16 v[92:95], v[156:159], v[206:209], v[92:95]
	v_mfma_f32_16x16x32_bf16 v[116:119], v[148:151], v[214:217], v[116:119]
	v_mfma_f32_16x16x32_bf16 v[84:87], v[156:159], v[214:217], v[84:87]
	v_mfma_f32_16x16x32_bf16 v[112:115], v[148:151], v[222:225], v[112:115]
	v_mfma_f32_16x16x32_bf16 v[80:83], v[156:159], v[222:225], v[80:83]
	s_setprio 0
	s_setprio 1
	v_mfma_f32_16x16x32_bf16 v[108:111], v[160:163], v[180:183], v[108:111]
	v_mfma_f32_16x16x32_bf16 v[76:79], v[172:175], v[180:183], v[76:79]
	v_mfma_f32_16x16x32_bf16 v[100:103], v[160:163], v[202:205], v[100:103]
	v_mfma_f32_16x16x32_bf16 v[68:71], v[172:175], v[202:205], v[68:71]
	v_mfma_f32_16x16x32_bf16 v[96:99], v[160:163], v[210:213], v[96:99]
	v_mfma_f32_16x16x32_bf16 v[64:67], v[172:175], v[210:213], v[64:67]
	v_mfma_f32_16x16x32_bf16 v[104:107], v[160:163], v[218:221], v[104:107]
	v_mfma_f32_16x16x32_bf16 v[72:75], v[172:175], v[218:221], v[72:75]
	v_mfma_f32_16x16x32_bf16 v[108:111], v[168:171], v[198:201], v[108:111]
	v_mfma_f32_16x16x32_bf16 v[76:79], v[176:179], v[198:201], v[76:79]
	v_mfma_f32_16x16x32_bf16 v[100:103], v[168:171], v[206:209], v[100:103]
	v_mfma_f32_16x16x32_bf16 v[68:71], v[176:179], v[206:209], v[68:71]
	v_mfma_f32_16x16x32_bf16 v[96:99], v[168:171], v[214:217], v[96:99]
	v_mfma_f32_16x16x32_bf16 v[64:67], v[176:179], v[214:217], v[64:67]
	v_mfma_f32_16x16x32_bf16 v[104:107], v[168:171], v[222:225], v[104:107]
	v_mfma_f32_16x16x32_bf16 v[72:75], v[176:179], v[222:225], v[72:75]
	s_setprio 0
	s_barrier
	s_add_u32 s98, s68, 0x80
	s_addc_u32 s99, s69, 0
	s_add_u32 s100, s70, 0x80
	s_addc_u32 s101, s71, 0
	s_add_i32 s97, s88, s78
	s_mov_b32 m0, s97
	ds_read_b128 v[180:183], v195 offset:16384
	ds_read_b128 v[198:201], v195 offset:17408
	ds_read_b128 v[202:205], v195 offset:18432
	ds_read_b128 v[206:209], v195 offset:19456
	ds_read_b128 v[210:213], v195 offset:20480
	ds_read_b128 v[214:217], v195 offset:21504
	ds_read_b128 v[218:221], v195 offset:22528
	ds_read_b128 v[222:225], v195 offset:23552
	global_load_lds_dwordx4 v132, s[68:69]
	s_add_i32 m0, s97, 0x2000
	s_add_u32 vcc_lo, s68, 0x80000
	s_addc_u32 vcc_hi, s69, 0
	s_add_i32 s97, s89, s78
	global_load_lds_dwordx4 v128, s[68:69]
	s_mov_b32 m0, s97
	s_nop 0
	global_load_lds_dwordx4 v132, vcc
	s_add_i32 m0, s97, 0x2000
	s_nop 0
	global_load_lds_dwordx4 v128, vcc
	s_mov_b32 m0, s80
	s_nop 0
	global_load_lds_dwordx4 v134, s[70:71]
	s_mov_b32 m0, s81
	s_nop 0
	global_load_lds_dwordx4 v130, s[70:71]
	s_waitcnt vmcnt(8)
	s_waitcnt lgkmcnt(0)
	s_barrier
	s_setprio 1
	s_waitcnt lgkmcnt(0)
	v_mfma_f32_16x16x32_bf16 v[56:59], v[144:147], v[180:183], v[56:59]
	v_mfma_f32_16x16x32_bf16 v[24:27], v[152:155], v[180:183], v[24:27]
	v_mfma_f32_16x16x32_bf16 v[60:63], v[144:147], v[202:205], v[60:63]
	v_mfma_f32_16x16x32_bf16 v[28:31], v[152:155], v[202:205], v[28:31]
	v_mfma_f32_16x16x32_bf16 v[52:55], v[144:147], v[210:213], v[52:55]
	v_mfma_f32_16x16x32_bf16 v[20:23], v[152:155], v[210:213], v[20:23]
	v_mfma_f32_16x16x32_bf16 v[48:51], v[144:147], v[218:221], v[48:51]
	v_mfma_f32_16x16x32_bf16 v[16:19], v[152:155], v[218:221], v[16:19]
	v_mfma_f32_16x16x32_bf16 v[56:59], v[148:151], v[198:201], v[56:59]
	v_mfma_f32_16x16x32_bf16 v[24:27], v[156:159], v[198:201], v[24:27]
	v_mfma_f32_16x16x32_bf16 v[60:63], v[148:151], v[206:209], v[60:63]
	v_mfma_f32_16x16x32_bf16 v[28:31], v[156:159], v[206:209], v[28:31]
	v_mfma_f32_16x16x32_bf16 v[52:55], v[148:151], v[214:217], v[52:55]
	v_mfma_f32_16x16x32_bf16 v[20:23], v[156:159], v[214:217], v[20:23]
	v_mfma_f32_16x16x32_bf16 v[48:51], v[148:151], v[222:225], v[48:51]
	v_mfma_f32_16x16x32_bf16 v[16:19], v[156:159], v[222:225], v[16:19]
	s_setprio 0
	s_setprio 1
	v_mfma_f32_16x16x32_bf16 v[44:47], v[160:163], v[180:183], v[44:47]
	v_mfma_f32_16x16x32_bf16 v[12:15], v[172:175], v[180:183], v[12:15]
	v_mfma_f32_16x16x32_bf16 v[36:39], v[160:163], v[202:205], v[36:39]
	v_mfma_f32_16x16x32_bf16 v[4:7], v[172:175], v[202:205], v[4:7]
	v_mfma_f32_16x16x32_bf16 v[32:35], v[160:163], v[210:213], v[32:35]
	v_mfma_f32_16x16x32_bf16 v[0:3], v[172:175], v[210:213], v[0:3]
	v_mfma_f32_16x16x32_bf16 v[40:43], v[160:163], v[218:221], v[40:43]
	v_mfma_f32_16x16x32_bf16 v[8:11], v[172:175], v[218:221], v[8:11]
	v_mfma_f32_16x16x32_bf16 v[44:47], v[168:171], v[198:201], v[44:47]
	v_mfma_f32_16x16x32_bf16 v[12:15], v[176:179], v[198:201], v[12:15]
	v_mfma_f32_16x16x32_bf16 v[36:39], v[168:171], v[206:209], v[36:39]
	v_mfma_f32_16x16x32_bf16 v[4:7], v[176:179], v[206:209], v[4:7]
	v_mfma_f32_16x16x32_bf16 v[32:35], v[168:171], v[214:217], v[32:35]
	v_mfma_f32_16x16x32_bf16 v[0:3], v[176:179], v[214:217], v[0:3]
	v_mfma_f32_16x16x32_bf16 v[40:43], v[168:171], v[222:225], v[40:43]
	v_mfma_f32_16x16x32_bf16 v[8:11], v[176:179], v[222:225], v[8:11]
	s_setprio 0
	s_barrier
; #define PG8_STAGE(bufoff, gbase, voff) do { _Pragma("unroll") for (int _i = 0; _i < 2; ++_i) \
;         __builtin_amdgcn_global_load_lds((const unsigned*)((const char*)(gbase) + (voff)[_i]), (PG8_LAS unsigned*)(lds + (bufoff) + ldsw + _i * 8192), 16, 0, 0); } while (0)
; #define PG8_LDA(dst, b, h) do { _Pragma("unroll") for (int m = 0; m < 4; ++m) _Pragma("unroll") for (int k = 0; k < 2; ++k) dst[m][k] = *(const PG8_LAS bf16x8*)(lds + PG8_SA(b, h) + aoff + m * 2048 + k * 1024); } while (0)
; #define PG8_LDB(dst, b, h) do { _Pragma("unroll") for (int n = 0; n < 2; ++n) _Pragma("unroll") for (int k = 0; k < 2; ++k) dst[n][k] = *(const PG8_LAS bf16x8*)(lds + PG8_SB(b, h) + boff + n * 2048 + k * 1024); } while (0)
; #define PG8_MMA(ai, bj, At, Bt) do { __builtin_amdgcn_s_setprio(1); _Pragma("unroll") for (int m = 0; m < 4; ++m) _Pragma("unroll") for (int n = 0; n < 2; ++n) _Pragma("unroll") for (int k = 0; k < 2; ++k) \
;         acc[ai][bj][m][n] = __builtin_amdgcn_mfma_f32_16x16x32_bf16(Bt[n][k], At[m][k], acc[ai][bj][m][n], 0, 0, 0); __builtin_amdgcn_s_setprio(0); } while (0)
; #define PG8_WAIT_V(n) asm volatile("s_waitcnt vmcnt(" #n ")" ::: "memory")
; #define PG8_WAIT_L(n) asm volatile("s_waitcnt lgkmcnt(" #n ")" ::: "memory")
; #define PG8_BAR __builtin_amdgcn_s_barrier()
; #define PG8_SCHED __builtin_amdgcn_sched_barrier(0)
; template <class Epi, class Sched, bool ALIGN_EPI = false, bool SP2 = false>
; __device__ __forceinline__ void gemm_phase(PG8_LAS unsigned char* lds, const Gemm g, const Sched& S, const Epi& E) {
;     ...
;             PG8_LDB(B0, 1, 0); PG8_LDB(B1, 1, 1); PG8_SCHED; PG8_LDA(At, 1, 0); PG8_STAGE(PG8_SA(0, 1), a2 + hstep, voffA);
;             PG8_WAIT_V(8); PG8_WAIT_L(0); PG8_BAR; PG8_MMA(0, 0, At, B0); PG8_MMA(0, 1, At, B1); PG8_BAR; PG8_SCHED;
;             PG8_LDA(At, 1, 1); PG8_STAGE(PG8_SB(1, 0), b3, voffB); PG8_STAGE(PG8_SB(1, 1), b3 + hstep, voffB); PG8_STAGE(PG8_SA(1, 0), a3, voffA);
;             PG8_WAIT_V(8); PG8_WAIT_L(0); PG8_BAR; PG8_MMA(1, 0, At, B0); PG8_MMA(1, 1, At, B1); PG8_BAR; PG8_SCHED;
	s_add_i32 s97, 0, 0x18000
	s_add_i32 vcc_lo, 0, 0x1c000
	v_add_u32_e32 v156, s97, v190
	v_add_u32_e32 v176, vcc_lo, v190
	ds_read_b128 v[144:147], v156
	ds_read_b128 v[148:151], v156 offset:1024
	ds_read_b128 v[152:155], v156 offset:2048
	ds_read_b128 v[156:159], v156 offset:3072
	ds_read_b128 v[160:163], v176
	ds_read_b128 v[168:171], v176 offset:1024
	ds_read_b128 v[172:175], v176 offset:2048
	ds_read_b128 v[176:179], v176 offset:3072
	s_add_u32 s70, s70, 0x80000
	s_addc_u32 s71, s71, 0
	s_mov_b32 m0, s82
	ds_read_b128 v[180:183], v195 offset:32768
	ds_read_b128 v[198:201], v195 offset:33792
	ds_read_b128 v[202:205], v195 offset:34816
	ds_read_b128 v[206:209], v195 offset:35840
	ds_read_b128 v[210:213], v195 offset:36864
	ds_read_b128 v[214:217], v195 offset:37888
	ds_read_b128 v[218:221], v195 offset:38912
	ds_read_b128 v[222:225], v195 offset:39936
	global_load_lds_dwordx4 v134, s[70:71]
	s_mov_b32 m0, s83
	s_nop 0
	global_load_lds_dwordx4 v130, s[70:71]
	s_waitcnt vmcnt(8)
	s_waitcnt lgkmcnt(0)
	s_barrier
	s_setprio 1
	s_waitcnt lgkmcnt(0)
	v_mfma_f32_16x16x32_bf16 v[124:127], v[144:147], v[180:183], v[124:127]
	v_mfma_f32_16x16x32_bf16 v[88:91], v[152:155], v[180:183], v[88:91]
	v_mfma_f32_16x16x32_bf16 v[120:123], v[144:147], v[202:205], v[120:123]
	v_mfma_f32_16x16x32_bf16 v[92:95], v[152:155], v[202:205], v[92:95]
	v_mfma_f32_16x16x32_bf16 v[116:119], v[144:147], v[210:213], v[116:119]
	v_mfma_f32_16x16x32_bf16 v[84:87], v[152:155], v[210:213], v[84:87]
	v_mfma_f32_16x16x32_bf16 v[112:115], v[144:147], v[218:221], v[112:115]
	v_mfma_f32_16x16x32_bf16 v[80:83], v[152:155], v[218:221], v[80:83]
	v_mfma_f32_16x16x32_bf16 v[124:127], v[148:151], v[198:201], v[124:127]
	v_mfma_f32_16x16x32_bf16 v[88:91], v[156:159], v[198:201], v[88:91]
	v_mfma_f32_16x16x32_bf16 v[120:123], v[148:151], v[206:209], v[120:123]
	v_mfma_f32_16x16x32_bf16 v[92:95], v[156:159], v[206:209], v[92:95]
	v_mfma_f32_16x16x32_bf16 v[116:119], v[148:151], v[214:217], v[116:119]
	v_mfma_f32_16x16x32_bf16 v[84:87], v[156:159], v[214:217], v[84:87]
	v_mfma_f32_16x16x32_bf16 v[112:115], v[148:151], v[222:225], v[112:115]
	v_mfma_f32_16x16x32_bf16 v[80:83], v[156:159], v[222:225], v[80:83]
	s_setprio 0
	s_setprio 1
	v_mfma_f32_16x16x32_bf16 v[108:111], v[160:163], v[180:183], v[108:111]
	v_mfma_f32_16x16x32_bf16 v[76:79], v[172:175], v[180:183], v[76:79]
	v_mfma_f32_16x16x32_bf16 v[100:103], v[160:163], v[202:205], v[100:103]
	v_mfma_f32_16x16x32_bf16 v[68:71], v[172:175], v[202:205], v[68:71]
	v_mfma_f32_16x16x32_bf16 v[96:99], v[160:163], v[210:213], v[96:99]
	v_mfma_f32_16x16x32_bf16 v[64:67], v[172:175], v[210:213], v[64:67]
	v_mfma_f32_16x16x32_bf16 v[104:107], v[160:163], v[218:221], v[104:107]
	v_mfma_f32_16x16x32_bf16 v[72:75], v[172:175], v[218:221], v[72:75]
	v_mfma_f32_16x16x32_bf16 v[108:111], v[168:171], v[198:201], v[108:111]
	v_mfma_f32_16x16x32_bf16 v[76:79], v[176:179], v[198:201], v[76:79]
	v_mfma_f32_16x16x32_bf16 v[100:103], v[168:171], v[206:209], v[100:103]
	v_mfma_f32_16x16x32_bf16 v[68:71], v[176:179], v[206:209], v[68:71]
	v_mfma_f32_16x16x32_bf16 v[96:99], v[168:171], v[214:217], v[96:99]
	v_mfma_f32_16x16x32_bf16 v[64:67], v[176:179], v[214:217], v[64:67]
	v_mfma_f32_16x16x32_bf16 v[104:107], v[168:171], v[222:225], v[104:107]
	v_mfma_f32_16x16x32_bf16 v[72:75], v[176:179], v[222:225], v[72:75]
	s_setprio 0
	s_barrier
	s_add_i32 s70, s97, s78
	s_mov_b32 m0, s70
	ds_read_b128 v[180:183], v195 offset:49152
	ds_read_b128 v[198:201], v195 offset:50176
	ds_read_b128 v[202:205], v195 offset:51200
	ds_read_b128 v[206:209], v195 offset:52224
	ds_read_b128 v[210:213], v195 offset:53248
	ds_read_b128 v[214:217], v195 offset:54272
	ds_read_b128 v[218:221], v195 offset:55296
	ds_read_b128 v[222:225], v195 offset:56320
	global_load_lds_dwordx4 v132, s[98:99]
	s_add_i32 m0, s70, 0x2000
	s_add_u32 s68, s68, 0x80080
	s_addc_u32 s69, s69, 0
	s_add_i32 s70, vcc_lo, s78
	global_load_lds_dwordx4 v128, s[98:99]
	s_mov_b32 m0, s70
	s_nop 0
	global_load_lds_dwordx4 v132, s[68:69]
	s_add_i32 m0, s70, 0x2000
	s_nop 0
	global_load_lds_dwordx4 v128, s[68:69]
	s_mov_b32 m0, s86
	s_nop 0
	global_load_lds_dwordx4 v134, s[100:101]
	s_mov_b32 m0, s87
	s_nop 0
	global_load_lds_dwordx4 v130, s[100:101]
	s_waitcnt vmcnt(8)
	s_waitcnt lgkmcnt(0)
	s_barrier
	s_setprio 1
	s_waitcnt lgkmcnt(0)
	v_mfma_f32_16x16x32_bf16 v[56:59], v[144:147], v[180:183], v[56:59]
	v_mfma_f32_16x16x32_bf16 v[24:27], v[152:155], v[180:183], v[24:27]
	v_mfma_f32_16x16x32_bf16 v[60:63], v[144:147], v[202:205], v[60:63]
	v_mfma_f32_16x16x32_bf16 v[28:31], v[152:155], v[202:205], v[28:31]
	v_mfma_f32_16x16x32_bf16 v[52:55], v[144:147], v[210:213], v[52:55]
	v_mfma_f32_16x16x32_bf16 v[20:23], v[152:155], v[210:213], v[20:23]
	v_mfma_f32_16x16x32_bf16 v[48:51], v[144:147], v[218:221], v[48:51]
	v_mfma_f32_16x16x32_bf16 v[16:19], v[152:155], v[218:221], v[16:19]
	v_mfma_f32_16x16x32_bf16 v[56:59], v[148:151], v[198:201], v[56:59]
	v_mfma_f32_16x16x32_bf16 v[24:27], v[156:159], v[198:201], v[24:27]
	v_mfma_f32_16x16x32_bf16 v[60:63], v[148:151], v[206:209], v[60:63]
	v_mfma_f32_16x16x32_bf16 v[28:31], v[156:159], v[206:209], v[28:31]
	v_mfma_f32_16x16x32_bf16 v[52:55], v[148:151], v[214:217], v[52:55]
	v_mfma_f32_16x16x32_bf16 v[20:23], v[156:159], v[214:217], v[20:23]
	v_mfma_f32_16x16x32_bf16 v[48:51], v[148:151], v[222:225], v[48:51]
	v_mfma_f32_16x16x32_bf16 v[16:19], v[156:159], v[222:225], v[16:19]
	s_setprio 0
	s_setprio 1
	v_mfma_f32_16x16x32_bf16 v[44:47], v[160:163], v[180:183], v[44:47]
	v_mfma_f32_16x16x32_bf16 v[12:15], v[172:175], v[180:183], v[12:15]
	v_mfma_f32_16x16x32_bf16 v[36:39], v[160:163], v[202:205], v[36:39]
	v_mfma_f32_16x16x32_bf16 v[4:7], v[172:175], v[202:205], v[4:7]
	v_mfma_f32_16x16x32_bf16 v[32:35], v[160:163], v[210:213], v[32:35]
	v_mfma_f32_16x16x32_bf16 v[0:3], v[172:175], v[210:213], v[0:3]
	v_mfma_f32_16x16x32_bf16 v[40:43], v[160:163], v[218:221], v[40:43]
	v_mfma_f32_16x16x32_bf16 v[8:11], v[172:175], v[218:221], v[8:11]
	v_mfma_f32_16x16x32_bf16 v[44:47], v[168:171], v[198:201], v[44:47]
	v_mfma_f32_16x16x32_bf16 v[12:15], v[176:179], v[198:201], v[12:15]
	v_mfma_f32_16x16x32_bf16 v[36:39], v[168:171], v[206:209], v[36:39]
	v_mfma_f32_16x16x32_bf16 v[4:7], v[176:179], v[206:209], v[4:7]
	v_mfma_f32_16x16x32_bf16 v[32:35], v[168:171], v[214:217], v[32:35]
	v_mfma_f32_16x16x32_bf16 v[0:3], v[176:179], v[214:217], v[0:3]
	v_mfma_f32_16x16x32_bf16 v[40:43], v[168:171], v[222:225], v[40:43]
	v_mfma_f32_16x16x32_bf16 v[8:11], v[176:179], v[222:225], v[8:11]
	s_setprio 0
	s_barrier
	s_add_i32 s96, s96, 2
	s_add_u32 s94, s94, 0x100
	s_addc_u32 s95, s95, 0
	s_add_u32 s66, s66, 0x100
	s_addc_u32 s67, s67, 0
	s_cmp_lt_u32 s96, 30
	s_cbranch_scc1 .LBB0_644
	s_andn2_b64 vcc, exec, s[46:47]
	s_cbranch_vccnz .LBB0_647
	s_barrier

; #define PG8_STAGE(bufoff, gbase, voff) do { _Pragma("unroll") for (int _i = 0; _i < 2; ++_i) \
;         __builtin_amdgcn_global_load_lds((const unsigned*)((const char*)(gbase) + (voff)[_i]), (PG8_LAS unsigned*)(lds + (bufoff) + ldsw + _i * 8192), 16, 0, 0); } while (0)
; #define PG8_LDA(dst, b, h) do { _Pragma("unroll") for (int m = 0; m < 4; ++m) _Pragma("unroll") for (int k = 0; k < 2; ++k) dst[m][k] = *(const PG8_LAS bf16x8*)(lds + PG8_SA(b, h) + aoff + m * 2048 + k * 1024); } while (0)
; #define PG8_LDB(dst, b, h) do { _Pragma("unroll") for (int n = 0; n < 2; ++n) _Pragma("unroll") for (int k = 0; k < 2; ++k) dst[n][k] = *(const PG8_LAS bf16x8*)(lds + PG8_SB(b, h) + boff + n * 2048 + k * 1024); } while (0)
; #define PG8_MMA(ai, bj, At, Bt) do { __builtin_amdgcn_s_setprio(1); _Pragma("unroll") for (int m = 0; m < 4; ++m) _Pragma("unroll") for (int n = 0; n < 2; ++n) _Pragma("unroll") for (int k = 0; k < 2; ++k) \
;         acc[ai][bj][m][n] = __builtin_amdgcn_mfma_f32_16x16x32_bf16(Bt[n][k], At[m][k], acc[ai][bj][m][n], 0, 0, 0); __builtin_amdgcn_s_setprio(0); } while (0)
; #define PG8_WAIT_V(n) asm volatile("s_waitcnt vmcnt(" #n ")" ::: "memory")
; #define PG8_WAIT_L(n) asm volatile("s_waitcnt lgkmcnt(" #n ")" ::: "memory")
; #define PG8_BAR __builtin_amdgcn_s_barrier()
; #define PG8_SCHED __builtin_amdgcn_sched_barrier(0)
; template <class Epi, class Sched, bool ALIGN_EPI = false, bool SP2 = false>
; __device__ __forceinline__ void gemm_phase(PG8_LAS unsigned char* lds, const Gemm g, const Sched& S, const Epi& E) {
;     ...
;             const char* a2 = last ? nA : cA + (size_t)(t + 2) * kstep; const char* b2 = last ? nB : cB + (size_t)(t + 2) * kstep;
;             const char* a3 = a2 + kstep; const char* b3 = b2 + kstep;
;             if (last && has_next) S.a_ready(nxt);
;             if constexpr (SP2) {
;             PG8_LDB(B0, 0, 0); PG8_LDB(B1, 0, 1); PG8_SCHED; PG8_LDA(At, 0, 0); PG8_STAGE(PG8_SA(1, 1), a1 + hstep, voffA);
;             PG8_WAIT_V(8); PG8_WAIT_L(0); PG8_BAR; PG8_MMA(0, 0, At, B0); PG8_MMA(0, 1, At, B1); PG8_BAR; PG8_SCHED;
;             PG8_LDA(At, 0, 1); PG8_STAGE(PG8_SB(0, 0), b2, voffB); PG8_STAGE(PG8_SB(0, 1), b2 + hstep, voffB); PG8_STAGE(PG8_SA(0, 0), a2, voffA);
;             PG8_WAIT_V(8); PG8_WAIT_L(0); PG8_BAR; PG8_MMA(1, 0, At, B0); PG8_MMA(1, 1, At, B1); PG8_BAR; PG8_SCHED;
.LBB0_797:
	v_add_u32_e32 v171, s56, v166
	ds_read_b128 v[160:163], v169
	ds_read_b128 v[172:175], v169 offset:1024
	ds_read_b128 v[176:179], v169 offset:2048
	ds_read_b128 v[180:183], v169 offset:3072
	ds_read_b128 v[188:191], v171
	ds_read_b128 v[192:195], v171 offset:1024
	ds_read_b128 v[196:199], v171 offset:2048
	ds_read_b128 v[200:203], v171 offset:3072
	s_add_u32 s40, s38, 0x100
	s_addc_u32 s41, s39, 0
	s_cmpk_eq_i32 s61, 0x52
	s_cselect_b32 s45, s35, s41
	s_cselect_b32 s44, s34, s40
	s_cselect_b32 s43, s9, s60
	s_cselect_b32 s42, s8, s37
	s_add_i32 m0, s48, 0xc000
	ds_read_b128 v[204:207], v170
	ds_read_b128 v[208:211], v170 offset:1024
	ds_read_b128 v[212:215], v170 offset:2048
	ds_read_b128 v[216:219], v170 offset:3072
	ds_read_b128 v[220:223], v170 offset:4096
	ds_read_b128 v[224:227], v170 offset:5120
	ds_read_b128 v[228:231], v170 offset:6144
	ds_read_b128 v[232:235], v170 offset:7168
	global_load_lds_dwordx4 v154, s[38:39]
	s_add_i32 m0, s48, 0xe000
	s_nop 0
	global_load_lds_dwordx4 v152, s[38:39]
	s_waitcnt vmcnt(8)
	s_waitcnt lgkmcnt(0)
	s_barrier
	s_setprio 1
	s_waitcnt lgkmcnt(0)
	v_mfma_f32_16x16x32_bf16 v[124:127], v[160:163], v[204:207], v[124:127]
	v_mfma_f32_16x16x32_bf16 v[120:123], v[176:179], v[204:207], v[120:123]
	v_mfma_f32_16x16x32_bf16 v[108:111], v[160:163], v[212:215], v[108:111]
	v_mfma_f32_16x16x32_bf16 v[104:107], v[176:179], v[212:215], v[104:107]
	v_mfma_f32_16x16x32_bf16 v[92:95], v[160:163], v[220:223], v[92:95]
	v_mfma_f32_16x16x32_bf16 v[88:91], v[176:179], v[220:223], v[88:91]
	v_mfma_f32_16x16x32_bf16 v[76:79], v[160:163], v[228:231], v[76:79]
	v_mfma_f32_16x16x32_bf16 v[72:75], v[176:179], v[228:231], v[72:75]
	v_mfma_f32_16x16x32_bf16 v[124:127], v[172:175], v[208:211], v[124:127]
	v_mfma_f32_16x16x32_bf16 v[120:123], v[180:183], v[208:211], v[120:123]
	v_mfma_f32_16x16x32_bf16 v[108:111], v[172:175], v[216:219], v[108:111]
	v_mfma_f32_16x16x32_bf16 v[104:107], v[180:183], v[216:219], v[104:107]
	v_mfma_f32_16x16x32_bf16 v[92:95], v[172:175], v[224:227], v[92:95]
	v_mfma_f32_16x16x32_bf16 v[88:91], v[180:183], v[224:227], v[88:91]
	v_mfma_f32_16x16x32_bf16 v[76:79], v[172:175], v[232:235], v[76:79]
	v_mfma_f32_16x16x32_bf16 v[72:75], v[180:183], v[232:235], v[72:75]
	s_setprio 0
	s_setprio 1
	v_mfma_f32_16x16x32_bf16 v[116:119], v[188:191], v[204:207], v[116:119]
	v_mfma_f32_16x16x32_bf16 v[112:115], v[196:199], v[204:207], v[112:115]
	v_mfma_f32_16x16x32_bf16 v[100:103], v[188:191], v[212:215], v[100:103]
	v_mfma_f32_16x16x32_bf16 v[96:99], v[196:199], v[212:215], v[96:99]
	v_mfma_f32_16x16x32_bf16 v[84:87], v[188:191], v[220:223], v[84:87]
	v_mfma_f32_16x16x32_bf16 v[80:83], v[196:199], v[220:223], v[80:83]
	v_mfma_f32_16x16x32_bf16 v[68:71], v[188:191], v[228:231], v[68:71]
	v_mfma_f32_16x16x32_bf16 v[64:67], v[196:199], v[228:231], v[64:67]
	v_mfma_f32_16x16x32_bf16 v[116:119], v[192:195], v[208:211], v[116:119]
	v_mfma_f32_16x16x32_bf16 v[112:115], v[200:203], v[208:211], v[112:115]
	v_mfma_f32_16x16x32_bf16 v[100:103], v[192:195], v[216:219], v[100:103]
	v_mfma_f32_16x16x32_bf16 v[96:99], v[200:203], v[216:219], v[96:99]
	v_mfma_f32_16x16x32_bf16 v[84:87], v[192:195], v[224:227], v[84:87]
	v_mfma_f32_16x16x32_bf16 v[80:83], v[200:203], v[224:227], v[80:83]
	v_mfma_f32_16x16x32_bf16 v[68:71], v[192:195], v[232:235], v[68:71]
	v_mfma_f32_16x16x32_bf16 v[64:67], v[200:203], v[232:235], v[64:67]
	s_setprio 0
	s_barrier
	s_add_u32 s98, s42, 0x80
	s_addc_u32 s99, s43, 0
	s_add_u32 s100, s44, 0x80
	s_addc_u32 s101, s45, 0
	s_add_i32 s38, s55, s47
	s_mov_b32 m0, s38
	ds_read_b128 v[204:207], v170 offset:16384
	ds_read_b128 v[208:211], v170 offset:17408
	ds_read_b128 v[212:215], v170 offset:18432
	ds_read_b128 v[216:219], v170 offset:19456
	ds_read_b128 v[220:223], v170 offset:20480
	ds_read_b128 v[224:227], v170 offset:21504
	ds_read_b128 v[228:231], v170 offset:22528
	ds_read_b128 v[232:235], v170 offset:23552
	global_load_lds_dwordx4 v130, s[42:43]
	s_add_i32 m0, s38, 0x2000
	s_add_u32 s38, s42, 0x158000
	s_addc_u32 s39, s43, 0
	s_add_i32 s62, s56, s47
	global_load_lds_dwordx4 v134, s[42:43]
	s_mov_b32 m0, s62
	s_nop 0
	global_load_lds_dwordx4 v130, s[38:39]
	s_add_i32 m0, s62, 0x2000
	s_nop 0
	global_load_lds_dwordx4 v134, s[38:39]
	s_mov_b32 m0, s48
	s_nop 0
	global_load_lds_dwordx4 v128, s[44:45]
	s_mov_b32 m0, s49
	s_nop 0
	global_load_lds_dwordx4 v132, s[44:45]
	s_waitcnt vmcnt(8)
	s_waitcnt lgkmcnt(0)
	s_barrier
	s_setprio 1
	s_waitcnt lgkmcnt(0)
	v_mfma_f32_16x16x32_bf16 v[60:63], v[160:163], v[204:207], v[60:63]
	v_mfma_f32_16x16x32_bf16 v[56:59], v[176:179], v[204:207], v[56:59]
	v_mfma_f32_16x16x32_bf16 v[44:47], v[160:163], v[212:215], v[44:47]
	v_mfma_f32_16x16x32_bf16 v[40:43], v[176:179], v[212:215], v[40:43]
	v_mfma_f32_16x16x32_bf16 v[28:31], v[160:163], v[220:223], v[28:31]
	v_mfma_f32_16x16x32_bf16 v[24:27], v[176:179], v[220:223], v[24:27]
	v_mfma_f32_16x16x32_bf16 v[12:15], v[160:163], v[228:231], v[12:15]
	v_mfma_f32_16x16x32_bf16 v[8:11], v[176:179], v[228:231], v[8:11]
	v_mfma_f32_16x16x32_bf16 v[60:63], v[172:175], v[208:211], v[60:63]
	v_mfma_f32_16x16x32_bf16 v[56:59], v[180:183], v[208:211], v[56:59]
	v_mfma_f32_16x16x32_bf16 v[44:47], v[172:175], v[216:219], v[44:47]
	v_mfma_f32_16x16x32_bf16 v[40:43], v[180:183], v[216:219], v[40:43]
	v_mfma_f32_16x16x32_bf16 v[28:31], v[172:175], v[224:227], v[28:31]
	v_mfma_f32_16x16x32_bf16 v[24:27], v[180:183], v[224:227], v[24:27]
	v_mfma_f32_16x16x32_bf16 v[12:15], v[172:175], v[232:235], v[12:15]
	v_mfma_f32_16x16x32_bf16 v[8:11], v[180:183], v[232:235], v[8:11]
	s_setprio 0
	s_setprio 1
	v_mfma_f32_16x16x32_bf16 v[52:55], v[188:191], v[204:207], v[52:55]
	v_mfma_f32_16x16x32_bf16 v[48:51], v[196:199], v[204:207], v[48:51]
	v_mfma_f32_16x16x32_bf16 v[36:39], v[188:191], v[212:215], v[36:39]
	v_mfma_f32_16x16x32_bf16 v[32:35], v[196:199], v[212:215], v[32:35]
	v_mfma_f32_16x16x32_bf16 v[20:23], v[188:191], v[220:223], v[20:23]
	v_mfma_f32_16x16x32_bf16 v[16:19], v[196:199], v[220:223], v[16:19]
	v_mfma_f32_16x16x32_bf16 v[4:7], v[188:191], v[228:231], v[4:7]
	v_mfma_f32_16x16x32_bf16 v[0:3], v[196:199], v[228:231], v[0:3]
	v_mfma_f32_16x16x32_bf16 v[52:55], v[192:195], v[208:211], v[52:55]
	v_mfma_f32_16x16x32_bf16 v[48:51], v[200:203], v[208:211], v[48:51]
	v_mfma_f32_16x16x32_bf16 v[36:39], v[192:195], v[216:219], v[36:39]
	v_mfma_f32_16x16x32_bf16 v[32:35], v[200:203], v[216:219], v[32:35]
	v_mfma_f32_16x16x32_bf16 v[20:23], v[192:195], v[224:227], v[20:23]
	v_mfma_f32_16x16x32_bf16 v[16:19], v[200:203], v[224:227], v[16:19]
	v_mfma_f32_16x16x32_bf16 v[4:7], v[192:195], v[232:235], v[4:7]
	v_mfma_f32_16x16x32_bf16 v[0:3], v[200:203], v[232:235], v[0:3]
	s_setprio 0
	s_barrier
; #define PG8_STAGE(bufoff, gbase, voff) do { _Pragma("unroll") for (int _i = 0; _i < 2; ++_i) \
;         __builtin_amdgcn_global_load_lds((const unsigned*)((const char*)(gbase) + (voff)[_i]), (PG8_LAS unsigned*)(lds + (bufoff) + ldsw + _i * 8192), 16, 0, 0); } while (0)
; #define PG8_LDA(dst, b, h) do { _Pragma("unroll") for (int m = 0; m < 4; ++m) _Pragma("unroll") for (int k = 0; k < 2; ++k) dst[m][k] = *(const PG8_LAS bf16x8*)(lds + PG8_SA(b, h) + aoff + m * 2048 + k * 1024); } while (0)
; #define PG8_LDB(dst, b, h) do { _Pragma("unroll") for (int n = 0; n < 2; ++n) _Pragma("unroll") for (int k = 0; k < 2; ++k) dst[n][k] = *(const PG8_LAS bf16x8*)(lds + PG8_SB(b, h) + boff + n * 2048 + k * 1024); } while (0)
; #define PG8_MMA(ai, bj, At, Bt) do { __builtin_amdgcn_s_setprio(1); _Pragma("unroll") for (int m = 0; m < 4; ++m) _Pragma("unroll") for (int n = 0; n < 2; ++n) _Pragma("unroll") for (int k = 0; k < 2; ++k) \
;         acc[ai][bj][m][n] = __builtin_amdgcn_mfma_f32_16x16x32_bf16(Bt[n][k], At[m][k], acc[ai][bj][m][n], 0, 0, 0); __builtin_amdgcn_s_setprio(0); } while (0)
; #define PG8_WAIT_V(n) asm volatile("s_waitcnt vmcnt(" #n ")" ::: "memory")
; #define PG8_WAIT_L(n) asm volatile("s_waitcnt lgkmcnt(" #n ")" ::: "memory")
; #define PG8_BAR __builtin_amdgcn_s_barrier()
; #define PG8_SCHED __builtin_amdgcn_sched_barrier(0)
; template <class Epi, class Sched, bool ALIGN_EPI = false, bool SP2 = false>
; __device__ __forceinline__ void gemm_phase(PG8_LAS unsigned char* lds, const Gemm g, const Sched& S, const Epi& E) {
;     ...
;             PG8_LDB(B0, 1, 0); PG8_LDB(B1, 1, 1); PG8_SCHED; PG8_LDA(At, 1, 0); PG8_STAGE(PG8_SA(0, 1), a2 + hstep, voffA);
;             PG8_WAIT_V(8); PG8_WAIT_L(0); PG8_BAR; PG8_MMA(0, 0, At, B0); PG8_MMA(0, 1, At, B1); PG8_BAR; PG8_SCHED;
;             PG8_LDA(At, 1, 1); PG8_STAGE(PG8_SB(1, 0), b3, voffB); PG8_STAGE(PG8_SB(1, 1), b3 + hstep, voffB); PG8_STAGE(PG8_SA(1, 0), a3, voffA);
;             PG8_WAIT_V(8); PG8_WAIT_L(0); PG8_BAR; PG8_MMA(1, 0, At, B0); PG8_MMA(1, 1, At, B1); PG8_BAR; PG8_SCHED;
	s_add_i32 s62, 0, 0x18000
	v_add_u32_e32 v171, s62, v166
	s_add_i32 s63, 0, 0x1c000
	ds_read_b128 v[160:163], v171
	ds_read_b128 v[172:175], v171 offset:1024
	ds_read_b128 v[176:179], v171 offset:2048
	ds_read_b128 v[180:183], v171 offset:3072
	v_add_u32_e32 v171, s63, v166
	ds_read_b128 v[188:191], v171
	ds_read_b128 v[192:195], v171 offset:1024
	ds_read_b128 v[196:199], v171 offset:2048
	ds_read_b128 v[200:203], v171 offset:3072
	s_add_u32 s38, s44, 0x158000
	s_addc_u32 s39, s45, 0
	s_mov_b32 m0, s50
	ds_read_b128 v[204:207], v170 offset:32768
	ds_read_b128 v[208:211], v170 offset:33792
	ds_read_b128 v[212:215], v170 offset:34816
	ds_read_b128 v[216:219], v170 offset:35840
	ds_read_b128 v[220:223], v170 offset:36864
	ds_read_b128 v[224:227], v170 offset:37888
	ds_read_b128 v[228:231], v170 offset:38912
	ds_read_b128 v[232:235], v170 offset:39936
	global_load_lds_dwordx4 v128, s[38:39]
	s_mov_b32 m0, s51
	s_nop 0
	global_load_lds_dwordx4 v132, s[38:39]
	s_waitcnt vmcnt(8)
	s_waitcnt lgkmcnt(0)
	s_barrier
	s_setprio 1
	s_waitcnt lgkmcnt(0)
	v_mfma_f32_16x16x32_bf16 v[124:127], v[160:163], v[204:207], v[124:127]
	v_mfma_f32_16x16x32_bf16 v[120:123], v[176:179], v[204:207], v[120:123]
	v_mfma_f32_16x16x32_bf16 v[108:111], v[160:163], v[212:215], v[108:111]
	v_mfma_f32_16x16x32_bf16 v[104:107], v[176:179], v[212:215], v[104:107]
	v_mfma_f32_16x16x32_bf16 v[92:95], v[160:163], v[220:223], v[92:95]
	v_mfma_f32_16x16x32_bf16 v[88:91], v[176:179], v[220:223], v[88:91]
	v_mfma_f32_16x16x32_bf16 v[76:79], v[160:163], v[228:231], v[76:79]
	v_mfma_f32_16x16x32_bf16 v[72:75], v[176:179], v[228:231], v[72:75]
	v_mfma_f32_16x16x32_bf16 v[124:127], v[172:175], v[208:211], v[124:127]
	v_mfma_f32_16x16x32_bf16 v[120:123], v[180:183], v[208:211], v[120:123]
	v_mfma_f32_16x16x32_bf16 v[108:111], v[172:175], v[216:219], v[108:111]
	v_mfma_f32_16x16x32_bf16 v[104:107], v[180:183], v[216:219], v[104:107]
	v_mfma_f32_16x16x32_bf16 v[92:95], v[172:175], v[224:227], v[92:95]
	v_mfma_f32_16x16x32_bf16 v[88:91], v[180:183], v[224:227], v[88:91]
	v_mfma_f32_16x16x32_bf16 v[76:79], v[172:175], v[232:235], v[76:79]
	v_mfma_f32_16x16x32_bf16 v[72:75], v[180:183], v[232:235], v[72:75]
	s_setprio 0
	s_setprio 1
	v_mfma_f32_16x16x32_bf16 v[116:119], v[188:191], v[204:207], v[116:119]
	v_mfma_f32_16x16x32_bf16 v[112:115], v[196:199], v[204:207], v[112:115]
	v_mfma_f32_16x16x32_bf16 v[100:103], v[188:191], v[212:215], v[100:103]
	v_mfma_f32_16x16x32_bf16 v[96:99], v[196:199], v[212:215], v[96:99]
	v_mfma_f32_16x16x32_bf16 v[84:87], v[188:191], v[220:223], v[84:87]
	v_mfma_f32_16x16x32_bf16 v[80:83], v[196:199], v[220:223], v[80:83]
	v_mfma_f32_16x16x32_bf16 v[68:71], v[188:191], v[228:231], v[68:71]
	v_mfma_f32_16x16x32_bf16 v[64:67], v[196:199], v[228:231], v[64:67]
	v_mfma_f32_16x16x32_bf16 v[116:119], v[192:195], v[208:211], v[116:119]
	v_mfma_f32_16x16x32_bf16 v[112:115], v[200:203], v[208:211], v[112:115]
	v_mfma_f32_16x16x32_bf16 v[100:103], v[192:195], v[216:219], v[100:103]
	v_mfma_f32_16x16x32_bf16 v[96:99], v[200:203], v[216:219], v[96:99]
	v_mfma_f32_16x16x32_bf16 v[84:87], v[192:195], v[224:227], v[84:87]
	v_mfma_f32_16x16x32_bf16 v[80:83], v[200:203], v[224:227], v[80:83]
	v_mfma_f32_16x16x32_bf16 v[68:71], v[192:195], v[232:235], v[68:71]
	v_mfma_f32_16x16x32_bf16 v[64:67], v[200:203], v[232:235], v[64:67]
	s_setprio 0
	s_barrier
	s_add_i32 s38, s62, s47
	s_mov_b32 m0, s38
	ds_read_b128 v[204:207], v170 offset:49152
	ds_read_b128 v[208:211], v170 offset:50176
	ds_read_b128 v[212:215], v170 offset:51200
	ds_read_b128 v[216:219], v170 offset:52224
	ds_read_b128 v[220:223], v170 offset:53248
	ds_read_b128 v[224:227], v170 offset:54272
	ds_read_b128 v[228:231], v170 offset:55296
	ds_read_b128 v[232:235], v170 offset:56320
	global_load_lds_dwordx4 v130, s[98:99]
	s_add_i32 m0, s38, 0x2000
	s_add_u32 s38, s42, 0x158080
	s_addc_u32 s39, s43, 0
	s_add_i32 s42, s63, s47
	global_load_lds_dwordx4 v134, s[98:99]
	s_mov_b32 m0, s42
	s_nop 0
	global_load_lds_dwordx4 v130, s[38:39]
	s_add_i32 m0, s42, 0x2000
	s_nop 0
	global_load_lds_dwordx4 v134, s[38:39]
	s_mov_b32 m0, s53
	s_nop 0
	global_load_lds_dwordx4 v128, s[100:101]
	s_mov_b32 m0, s54
	s_nop 0
	global_load_lds_dwordx4 v132, s[100:101]
	s_waitcnt vmcnt(8)
	s_waitcnt lgkmcnt(0)
	s_barrier
	s_setprio 1
	s_waitcnt lgkmcnt(0)
	v_mfma_f32_16x16x32_bf16 v[60:63], v[160:163], v[204:207], v[60:63]
	v_mfma_f32_16x16x32_bf16 v[56:59], v[176:179], v[204:207], v[56:59]
	v_mfma_f32_16x16x32_bf16 v[44:47], v[160:163], v[212:215], v[44:47]
	v_mfma_f32_16x16x32_bf16 v[40:43], v[176:179], v[212:215], v[40:43]
	v_mfma_f32_16x16x32_bf16 v[28:31], v[160:163], v[220:223], v[28:31]
	v_mfma_f32_16x16x32_bf16 v[24:27], v[176:179], v[220:223], v[24:27]
	v_mfma_f32_16x16x32_bf16 v[12:15], v[160:163], v[228:231], v[12:15]
	v_mfma_f32_16x16x32_bf16 v[8:11], v[176:179], v[228:231], v[8:11]
	v_mfma_f32_16x16x32_bf16 v[60:63], v[172:175], v[208:211], v[60:63]
	v_mfma_f32_16x16x32_bf16 v[56:59], v[180:183], v[208:211], v[56:59]
	v_mfma_f32_16x16x32_bf16 v[44:47], v[172:175], v[216:219], v[44:47]
	v_mfma_f32_16x16x32_bf16 v[40:43], v[180:183], v[216:219], v[40:43]
	v_mfma_f32_16x16x32_bf16 v[28:31], v[172:175], v[224:227], v[28:31]
	v_mfma_f32_16x16x32_bf16 v[24:27], v[180:183], v[224:227], v[24:27]
	v_mfma_f32_16x16x32_bf16 v[12:15], v[172:175], v[232:235], v[12:15]
	v_mfma_f32_16x16x32_bf16 v[8:11], v[180:183], v[232:235], v[8:11]
	s_setprio 0
	s_setprio 1
	v_mfma_f32_16x16x32_bf16 v[52:55], v[188:191], v[204:207], v[52:55]
	v_mfma_f32_16x16x32_bf16 v[48:51], v[196:199], v[204:207], v[48:51]
	v_mfma_f32_16x16x32_bf16 v[36:39], v[188:191], v[212:215], v[36:39]
	v_mfma_f32_16x16x32_bf16 v[32:35], v[196:199], v[212:215], v[32:35]
	v_mfma_f32_16x16x32_bf16 v[20:23], v[188:191], v[220:223], v[20:23]
	v_mfma_f32_16x16x32_bf16 v[16:19], v[196:199], v[220:223], v[16:19]
	v_mfma_f32_16x16x32_bf16 v[4:7], v[188:191], v[228:231], v[4:7]
	v_mfma_f32_16x16x32_bf16 v[0:3], v[196:199], v[228:231], v[0:3]
	v_mfma_f32_16x16x32_bf16 v[52:55], v[192:195], v[208:211], v[52:55]
	v_mfma_f32_16x16x32_bf16 v[48:51], v[200:203], v[208:211], v[48:51]
	v_mfma_f32_16x16x32_bf16 v[36:39], v[192:195], v[216:219], v[36:39]
	v_mfma_f32_16x16x32_bf16 v[32:35], v[200:203], v[216:219], v[32:35]
	v_mfma_f32_16x16x32_bf16 v[20:23], v[192:195], v[224:227], v[20:23]
	v_mfma_f32_16x16x32_bf16 v[16:19], v[200:203], v[224:227], v[16:19]
	v_mfma_f32_16x16x32_bf16 v[4:7], v[192:195], v[232:235], v[4:7]
	v_mfma_f32_16x16x32_bf16 v[0:3], v[200:203], v[232:235], v[0:3]
	s_setprio 0
	s_barrier
	s_add_i32 s61, s61, 2
	s_add_u32 s37, s37, 0x100
	s_addc_u32 s60, s60, 0
	s_cmpk_lt_u32 s61, 0x54
	s_mov_b64 s[38:39], s[40:41]
	s_cbranch_scc1 .LBB0_797
	s_andn2_b64 vcc, exec, s[30:31]
	s_cbranch_vccnz .LBB0_800
	s_barrier

; __global__ void __launch_bounds__(NWAVES * 64, 2) mk_fwd(Args a_unused) {
	.amdhsa_kernel _Z6mk_fwd4Args
		.amdhsa_group_segment_fixed_size 0
		.amdhsa_private_segment_fixed_size 0
		.amdhsa_kernarg_size 416
		.amdhsa_user_sgpr_count 2
		.amdhsa_user_sgpr_dispatch_ptr 0
		.amdhsa_user_sgpr_queue_ptr 0
		.amdhsa_user_sgpr_kernarg_segment_ptr 1
		.amdhsa_user_sgpr_dispatch_id 0
		.amdhsa_user_sgpr_kernarg_preload_length 0
		.amdhsa_user_sgpr_kernarg_preload_offset 0
		.amdhsa_user_sgpr_private_segment_size 0
		.amdhsa_uses_dynamic_stack 0
		.amdhsa_enable_private_segment 0
		.amdhsa_system_sgpr_workgroup_id_x 1
		.amdhsa_system_sgpr_workgroup_id_y 0
		.amdhsa_system_sgpr_workgroup_id_z 0
		.amdhsa_system_sgpr_workgroup_info 0
		.amdhsa_system_vgpr_workitem_id 2
		.amdhsa_next_free_vgpr 254
		.amdhsa_next_free_sgpr 102
		.amdhsa_accum_offset 256
		.amdhsa_reserve_vcc 1
		.amdhsa_float_round_mode_32 0
		.amdhsa_float_round_mode_16_64 0
		.amdhsa_float_denorm_mode_32 3
		.amdhsa_float_denorm_mode_16_64 3
		.amdhsa_dx10_clamp 1
		.amdhsa_ieee_mode 1
		.amdhsa_fp16_overflow 0
		.amdhsa_tg_split 0
		.amdhsa_exception_fp_ieee_invalid_op 0
		.amdhsa_exception_fp_denorm_src 0
		.amdhsa_exception_fp_ieee_div_zero 0
		.amdhsa_exception_fp_ieee_overflow 0
		.amdhsa_exception_fp_ieee_underflow 0
		.amdhsa_exception_fp_ieee_inexact 0
		.amdhsa_exception_int_div_zero 0
	.end_amdhsa_kernel

; __global__ void __launch_bounds__(NWAVES * 64, 2) mk_fwd(Args a_unused) {
amdhsa.kernels:
  - .agpr_count:     0
    .args:
      - .offset:         0
        .size:           160
        .value_kind:     by_value
      - .offset:         160
        .size:           4
        .value_kind:     hidden_block_count_x
      - .offset:         164
        .size:           4
        .value_kind:     hidden_block_count_y
      - .offset:         168
        .size:           4
        .value_kind:     hidden_block_count_z
      - .offset:         172
        .size:           2
        .value_kind:     hidden_group_size_x
      - .offset:         174
        .size:           2
        .value_kind:     hidden_group_size_y
      - .offset:         176
        .size:           2
        .value_kind:     hidden_group_size_z
      - .offset:         178
        .size:           2
        .value_kind:     hidden_remainder_x
      - .offset:         180
        .size:           2
        .value_kind:     hidden_remainder_y
      - .offset:         182
        .size:           2
        .value_kind:     hidden_remainder_z
      - .offset:         200
        .size:           8
        .value_kind:     hidden_global_offset_x
      - .offset:         208
        .size:           8
        .value_kind:     hidden_global_offset_y
      - .offset:         216
        .size:           8
        .value_kind:     hidden_global_offset_z
      - .offset:         224
        .size:           2
        .value_kind:     hidden_grid_dims
      - .offset:         248
        .size:           8
        .value_kind:     hidden_multigrid_sync_arg
      - .offset:         280
        .size:           4
        .value_kind:     hidden_dynamic_lds_size
    .group_segment_fixed_size: 0
    .kernarg_segment_align: 8
    .kernarg_segment_size: 416
    .language:       OpenCL C
    .language_version:
      - 2
      - 0
    .max_flat_workgroup_size: 512
    .name:           _Z6mk_fwd4Args
    .private_segment_fixed_size: 0
    .sgpr_count:     108
    .sgpr_spill_count: 0
    .symbol:         _Z6mk_fwd4Args.kd
    .uniform_work_group_size: 1
    .uses_dynamic_stack: false
    .vgpr_count:     254
    .vgpr_spill_count: 0
    .wavefront_size: 64
